# SGU epilogue: the four U loads of each accumulator block issued together instead of one load + vmcnt(0) per store
# speedup vs baseline: 1.0346x; 1.0018x over previous
; #define LAS __attribute__((address_space(3)))
; __device__ __forceinline__ unsigned pk2(float lo, float hi) { return f2bf(lo) | (f2bf(hi) << 16); }
; __device__ __forceinline__ void sgu_phase(const LArgs& a, LAS unsigned char* lds) {
;     ...
;         const int g = u & 7, row0 = (u >> 3) * 128;
;         if (first || !same_g) {
;             const f32x4* wsrc = (const f32x4*)(a.in(I_ESW) + (size_t)g * 16384);
; #pragma unroll
;             for (int i = 0; i < 8; ++i) { const int idx = tid + NTHR * i; const f32x4 w = wsrc[idx]; const int pr_ = idx >> 5, q4 = (idx & 31) * 4;
;                 u32x2 pk; pk.x = pk2(w.x, w.y); pk.y = pk2(w.z, w.w); *(LAS u32x2*)(WsB + pr_ * ROWB + q4 * 2) = pk; }
;         }
;         const float ng0 = a.in(I_ESNG)[g * 128 + 2 * lane], ng1 = a.in(I_ESNG)[g * 128 + 2 * lane + 1], nb0 = a.in(I_ESNB)[g * 128 + 2 * lane], nb1 = a.in(I_ESNB)[g * 128 + 2 * lane + 1];
; #pragma unroll
;         for (int rr = 0; rr < 16; ++rr) {
;             const int r = wid * 16 + rr; const unsigned pk = *(const unsigned*)(Gg + (size_t)(row0 + r) * 1024 + g * 128 + 2 * lane);
;             const float x0 = bf2f(pk & 0xffffu), x1 = bf2f(pk >> 16);
;             const float mean = wave_sum(x0 + x1) * (1.f / 128.f); const float d0 = x0 - mean, d1 = x1 - mean;
;             const float rstd = 1.f / sqrtf(wave_sum(d0 * d0 + d1 * d1) * (1.f / 128.f) + 1e-5f);
.LBB0_311:
	s_and_b32 s5, s2, 0xffffff80
	v_add_u32_e32 v8, s5, v48
	v_add_u32_e32 v10, s5, v49
	v_add_u32_e32 v14, s5, v51
	s_lshl_b32 s48, s3, 8
	v_add_u32_e32 v0, s5, v45
	v_add_u32_e32 v2, s5, v46
	v_add_u32_e32 v6, s5, v47
	v_ashrrev_i32_e32 v9, 31, v8
	v_add_u32_e32 v12, s5, v50
	v_add_u32_e32 v16, s5, v52
	v_ashrrev_i32_e32 v11, 31, v10
	v_ashrrev_i32_e32 v15, 31, v14
	v_lshl_add_u64 v[4:5], v[38:39], 0, s[48:49]
	v_ashrrev_i32_e32 v1, 31, v0
	v_ashrrev_i32_e32 v3, 31, v2
	v_ashrrev_i32_e32 v7, 31, v6
	v_lshlrev_b64 v[8:9], 11, v[8:9]
	v_ashrrev_i32_e32 v13, 31, v12
	v_ashrrev_i32_e32 v17, 31, v16
	v_lshlrev_b64 v[10:11], 11, v[10:11]
	v_lshlrev_b64 v[14:15], 11, v[14:15]
	v_lshlrev_b64 v[0:1], 11, v[0:1]
	v_lshlrev_b64 v[2:3], 11, v[2:3]
	v_lshlrev_b64 v[6:7], 11, v[6:7]
	v_lshl_add_u64 v[8:9], v[4:5], 0, v[8:9]
	v_lshlrev_b64 v[12:13], 11, v[12:13]
	v_lshlrev_b64 v[16:17], 11, v[16:17]
	v_lshl_add_u64 v[10:11], v[4:5], 0, v[10:11]
	v_lshl_add_u64 v[14:15], v[4:5], 0, v[14:15]
	v_lshl_add_u64 v[0:1], v[4:5], 0, v[0:1]
	v_lshl_add_u64 v[2:3], v[4:5], 0, v[2:3]
	v_lshl_add_u64 v[6:7], v[4:5], 0, v[6:7]
	v_lshl_add_u64 v[12:13], v[4:5], 0, v[12:13]
	v_lshl_add_u64 v[16:17], v[4:5], 0, v[16:17]
	global_load_dword v8, v[8:9], off
	s_nop 0
	global_load_dword v23, v[10:11], off
	global_load_dword v28, v[12:13], off
	s_nop 0
	global_load_dword v10, v[14:15], off
	global_load_dword v11, v[16:17], off
	global_load_dword v9, v[6:7], off
	s_nop 0
	global_load_dword v15, v[2:3], off
	global_load_dword v18, v[0:1], off
	s_lshl_b32 s6, s3, 7
	v_or_b32_e32 v6, s6, v44
	v_lshlrev_b32_e32 v20, 2, v6
	v_mov_b32_e32 v14, s65
	ds_read2_b64 v[0:3], v14 offset0:15 offset1:16
	s_brev_b32 s12, 60
	s_mov_b32 s10, 0x7060302
	s_add_i32 s4, s4, s79
	s_add_i32 s2, s2, s91
	s_waitcnt lgkmcnt(0)
	v_readfirstlane_b32 s1, v1
	v_readfirstlane_b32 s0, v0
	v_readfirstlane_b32 s9, v3
	v_readfirstlane_b32 s8, v2
	s_cmpk_gt_i32 s4, 0x7ff
	s_waitcnt vmcnt(0)
	v_lshlrev_b32_e32 v13, 16, v8
	v_and_b32_e32 v17, 0xffff0000, v8
	v_add_f32_e32 v21, v13, v17
	ds_swizzle_b32 v26, v21 offset:swizzle(SWAP,1)
	v_lshlrev_b32_e32 v12, 16, v9
	v_lshlrev_b32_e32 v7, 16, v15
	v_lshlrev_b32_e32 v6, 16, v18
	v_and_b32_e32 v19, 0xffff0000, v15
	v_and_b32_e32 v18, 0xffff0000, v18
	v_and_b32_e32 v16, 0xffff0000, v9
	v_add_f32_e32 v8, v6, v18
	v_add_f32_e32 v9, v7, v19
	v_add_f32_e32 v15, v12, v16
	ds_swizzle_b32 v22, v8 offset:swizzle(SWAP,1)
	ds_swizzle_b32 v24, v9 offset:swizzle(SWAP,1)
	ds_swizzle_b32 v25, v15 offset:swizzle(SWAP,1)
	s_waitcnt lgkmcnt(2)
	v_add_f32_e32 v1, v8, v22
	s_waitcnt lgkmcnt(1)
	v_add_f32_e32 v8, v9, v24
	s_waitcnt lgkmcnt(0)
	v_add_f32_e32 v9, v15, v25
	v_add_f32_e32 v15, v21, v26
	ds_swizzle_b32 v21, v1 offset:swizzle(SWAP,2)
	ds_swizzle_b32 v22, v8 offset:swizzle(SWAP,2)
	ds_swizzle_b32 v24, v9 offset:swizzle(SWAP,2)
	ds_swizzle_b32 v25, v15 offset:swizzle(SWAP,2)
	s_waitcnt lgkmcnt(3)
	v_add_f32_e32 v0, v1, v21
	s_waitcnt lgkmcnt(2)
	v_add_f32_e32 v1, v8, v22
	s_waitcnt lgkmcnt(1)
	v_add_f32_e32 v8, v9, v24
	s_waitcnt lgkmcnt(0)
	v_add_f32_e32 v9, v15, v25
	ds_swizzle_b32 v15, v0 offset:swizzle(SWAP,4)
	ds_swizzle_b32 v21, v1 offset:swizzle(SWAP,4)
	ds_swizzle_b32 v22, v8 offset:swizzle(SWAP,4)
	ds_swizzle_b32 v24, v9 offset:swizzle(SWAP,4)
	s_waitcnt lgkmcnt(3)
	v_add_f32_e32 v0, v0, v15
	s_waitcnt lgkmcnt(2)
	v_add_f32_e32 v1, v1, v21
	s_waitcnt lgkmcnt(1)
	v_add_f32_e32 v3, v8, v22
	s_waitcnt lgkmcnt(0)
	v_add_f32_e32 v8, v9, v24
	ds_swizzle_b32 v9, v0 offset:swizzle(SWAP,8)
	ds_swizzle_b32 v15, v1 offset:swizzle(SWAP,8)
	ds_swizzle_b32 v22, v8 offset:swizzle(SWAP,8)
	ds_swizzle_b32 v21, v3 offset:swizzle(SWAP,8)
	s_waitcnt lgkmcnt(3)
	v_add_f32_e32 v9, v0, v9
	s_waitcnt lgkmcnt(2)
	v_add_f32_e32 v15, v1, v15
	s_waitcnt lgkmcnt(1)
	v_add_f32_e32 v8, v8, v22
	ds_swizzle_b32 v22, v9 offset:swizzle(SWAP,16)
	ds_swizzle_b32 v24, v15 offset:swizzle(SWAP,16)
	s_waitcnt lgkmcnt(2)
	v_add_f32_e32 v21, v3, v21
	ds_swizzle_b32 v26, v8 offset:swizzle(SWAP,16)
	ds_swizzle_b32 v25, v21 offset:swizzle(SWAP,16)
	s_waitcnt lgkmcnt(3)
	v_add_f32_e32 v9, v9, v22
	s_waitcnt lgkmcnt(2)
	v_add_f32_e32 v15, v15, v24
	v_readlane_b32 s3, v9, 32
	v_readlane_b32 s7, v15, 32
	global_load_dwordx2 v[0:1], v20, s[0:1]
	global_load_dwordx2 v[2:3], v20, s[8:9]
	s_waitcnt lgkmcnt(1)
	v_add_f32_e32 v24, v8, v26
	v_readlane_b32 s0, v9, 0
	v_readlane_b32 s1, v15, 0
	v_mov_b32_e32 v8, s3
	v_mov_b32_e32 v9, s7
	s_waitcnt lgkmcnt(0)
	v_add_f32_e32 v22, v21, v25
	v_pk_add_f32 v[20:21], s[0:1], v[8:9]
	v_readlane_b32 s0, v22, 0
	v_pk_fma_f32 v[8:9], v[20:21], s[12:13], v[6:7] op_sel_hi:[1,0,1] neg_lo:[1,0,0] neg_hi:[1,0,0]
	v_pk_fma_f32 v[6:7], v[20:21], s[12:13], v[18:19] op_sel_hi:[1,0,1] neg_lo:[1,0,0] neg_hi:[1,0,0]
	v_readlane_b32 s3, v22, 32
	v_mul_f32_e32 v15, v6, v6
	v_fmac_f32_e32 v15, v8, v8
	ds_swizzle_b32 v18, v15 offset:swizzle(SWAP,1)
	v_mul_f32_e32 v19, v7, v7
	v_fmac_f32_e32 v19, v9, v9
	ds_swizzle_b32 v20, v19 offset:swizzle(SWAP,1)
	v_readlane_b32 s7, v24, 32
	s_waitcnt lgkmcnt(1)
	v_add_f32_e32 v15, v15, v18
	ds_swizzle_b32 v18, v15 offset:swizzle(SWAP,2)
	v_readlane_b32 s1, v24, 0
	s_waitcnt lgkmcnt(1)
	v_add_f32_e32 v19, v19, v20
	ds_swizzle_b32 v20, v19 offset:swizzle(SWAP,2)
	s_waitcnt lgkmcnt(1)
	v_add_f32_e32 v15, v15, v18
	ds_swizzle_b32 v21, v15 offset:swizzle(SWAP,4)
	v_mov_b32_e32 v18, s3
	s_waitcnt lgkmcnt(1)
	v_add_f32_e32 v20, v19, v20
	ds_swizzle_b32 v22, v20 offset:swizzle(SWAP,4)
	v_mov_b32_e32 v19, s7
	s_waitcnt lgkmcnt(1)
	v_add_f32_e32 v15, v15, v21
	ds_swizzle_b32 v21, v15 offset:swizzle(SWAP,8)
	v_pk_add_f32 v[18:19], s[0:1], v[18:19]
	s_waitcnt lgkmcnt(1)
; #define LAS __attribute__((address_space(3)))
; __device__ __forceinline__ unsigned f2bf(float f) { unsigned u = __builtin_bit_cast(unsigned, f); return (u + 0x7fffu + ((u >> 16) & 1u)) >> 16; }
; __device__ __forceinline__ void sgu_phase(const LArgs& a, LAS unsigned char* lds) {
;     ...
;             const float mean = wave_sum(x0 + x1) * (1.f / 128.f); const float d0 = x0 - mean, d1 = x1 - mean;
;             const float rstd = 1.f / sqrtf(wave_sum(d0 * d0 + d1 * d1) * (1.f / 128.f) + 1e-5f);
;             *(LAS bf16*)(VVt + (2 * lane) * ROWB + r * 2) = (bf16)f2bf(d0 * rstd * ng0 + nb0); *(LAS bf16*)(VVt + (2 * lane + 1) * ROWB + r * 2) = (bf16)f2bf(d1 * rstd * ng1 + nb1);
	v_add_f32_e32 v20, v20, v22
	ds_swizzle_b32 v22, v20 offset:swizzle(SWAP,8)
	v_pk_fma_f32 v[12:13], v[18:19], s[12:13], v[12:13] op_sel_hi:[1,0,1] neg_lo:[1,0,0] neg_hi:[1,0,0]
	s_waitcnt lgkmcnt(1)
	v_add_f32_e32 v15, v15, v21
	ds_swizzle_b32 v21, v15 offset:swizzle(SWAP,16)
	v_pk_fma_f32 v[16:17], v[18:19], s[12:13], v[16:17] op_sel_hi:[1,0,1] neg_lo:[1,0,0] neg_hi:[1,0,0]
	s_waitcnt lgkmcnt(1)
	v_add_f32_e32 v18, v20, v22
	ds_swizzle_b32 v19, v18 offset:swizzle(SWAP,16)
	s_waitcnt lgkmcnt(1)
	v_add_f32_e32 v15, v15, v21
	s_nop 0
	v_readlane_b32 s1, v15, 32
	v_readlane_b32 s0, v15, 0
	s_waitcnt lgkmcnt(0)
	v_add_f32_e32 v18, v18, v19
	v_mov_b32_e32 v15, s1
	v_add_f32_e32 v15, s0, v15
	v_fmamk_f32 v15, v15, 0x3c000000, v197
	v_mul_f32_e32 v20, 0x4f800000, v15
	v_cmp_gt_f32_e32 vcc, s61, v15
	v_mul_f32_e32 v21, v16, v16
	v_fmac_f32_e32 v21, v12, v12
	v_cndmask_b32_e32 v15, v15, v20, vcc
	v_sqrt_f32_e32 v20, v15
	v_readlane_b32 s3, v18, 0
	v_add_u32_e32 v19, -1, v20
	v_add_u32_e32 v22, 1, v20
	v_fma_f32 v24, -v19, v20, v15
	v_fma_f32 v25, -v22, v20, v15
	v_cmp_ge_f32_e64 s[0:1], 0, v24
	s_nop 1
	v_cndmask_b32_e64 v19, v20, v19, s[0:1]
	v_cmp_lt_f32_e64 s[0:1], 0, v25
	s_nop 1
	v_cndmask_b32_e64 v19, v19, v22, s[0:1]
	ds_swizzle_b32 v22, v21 offset:swizzle(SWAP,1)
	v_mul_f32_e32 v20, 0x37800000, v19
	v_readlane_b32 s0, v18, 32
	v_cndmask_b32_e32 v19, v19, v20, vcc
	v_cmp_class_f32_e32 vcc, v15, v194
	s_waitcnt lgkmcnt(0)
	v_add_f32_e32 v21, v21, v22
	ds_swizzle_b32 v22, v21 offset:swizzle(SWAP,2)
	v_mov_b32_e32 v18, s0
	v_add_f32_e32 v18, s3, v18
	v_fmamk_f32 v18, v18, 0x3c000000, v197
	v_mul_f32_e32 v24, 0x4f800000, v18
	s_waitcnt lgkmcnt(0)
	v_add_f32_e32 v21, v21, v22
	ds_swizzle_b32 v22, v21 offset:swizzle(SWAP,4)
	v_cmp_gt_f32_e64 s[0:1], s61, v18
	v_cndmask_b32_e32 v15, v19, v15, vcc
	s_waitcnt lgkmcnt(0)
	v_add_f32_e32 v20, v21, v22
	ds_swizzle_b32 v21, v20 offset:swizzle(SWAP,8)
	v_cndmask_b32_e64 v18, v18, v24, s[0:1]
	v_sqrt_f32_e32 v24, v18
	s_waitcnt lgkmcnt(0)
	v_add_f32_e32 v20, v20, v21
	ds_swizzle_b32 v21, v20 offset:swizzle(SWAP,16)
	v_add_u32_e32 v19, -1, v24
	v_fma_f32 v22, -v19, v24, v18
	v_cmp_ge_f32_e32 vcc, 0, v22
	v_add_u32_e32 v22, 1, v24
	s_waitcnt lgkmcnt(0)
	v_add_f32_e32 v20, v20, v21
	v_mul_f32_e32 v21, v17, v17
	v_cndmask_b32_e32 v19, v24, v19, vcc
	v_fma_f32 v24, -v22, v24, v18
	v_fmac_f32_e32 v21, v13, v13
	v_cmp_lt_f32_e32 vcc, 0, v24
	ds_swizzle_b32 v24, v21 offset:swizzle(SWAP,1)
	v_readlane_b32 s7, v20, 32
	v_cndmask_b32_e32 v19, v19, v22, vcc
	v_readlane_b32 s3, v20, 0
	v_mov_b32_e32 v20, s7
	s_waitcnt lgkmcnt(0)
	v_add_f32_e32 v21, v21, v24
	ds_swizzle_b32 v24, v21 offset:swizzle(SWAP,2)
	v_mul_f32_e32 v22, 0x37800000, v19
	v_add_f32_e32 v20, s3, v20
	v_fmamk_f32 v20, v20, 0x3c000000, v197
	v_cndmask_b32_e64 v19, v19, v22, s[0:1]
	s_waitcnt lgkmcnt(0)
	v_add_f32_e32 v21, v21, v24
	ds_swizzle_b32 v24, v21 offset:swizzle(SWAP,4)
	v_mul_f32_e32 v25, 0x4f800000, v20
	v_cmp_gt_f32_e32 vcc, s61, v20
	v_cmp_class_f32_e64 s[0:1], v18, v194
	s_waitcnt lgkmcnt(0)
	v_add_f32_e32 v21, v21, v24
	ds_swizzle_b32 v22, v21 offset:swizzle(SWAP,8)
	v_cndmask_b32_e32 v20, v20, v25, vcc
	v_sqrt_f32_e32 v25, v20
	v_cndmask_b32_e64 v18, v19, v18, s[0:1]
	s_waitcnt lgkmcnt(0)
	v_add_f32_e32 v21, v21, v22
	ds_swizzle_b32 v22, v21 offset:swizzle(SWAP,16)
	v_add_u32_e32 v19, -1, v25
	v_fma_f32 v24, -v19, v25, v20
	v_cmp_ge_f32_e64 s[0:1], 0, v24
	v_add_u32_e32 v24, 1, v25
	s_waitcnt lgkmcnt(0)
	v_add_f32_e32 v21, v21, v22
	v_cndmask_b32_e64 v19, v25, v19, s[0:1]
	v_fma_f32 v25, -v24, v25, v20
	v_cmp_lt_f32_e64 s[0:1], 0, v25
	s_nop 1
	v_cndmask_b32_e64 v19, v19, v24, s[0:1]
	v_readlane_b32 s1, v21, 32
	v_readlane_b32 s0, v21, 0
	v_mul_f32_e32 v24, 0x37800000, v19
	v_mov_b32_e32 v21, s1
	v_add_f32_e32 v21, s0, v21
	v_fmamk_f32 v21, v21, 0x3c000000, v197
	v_mul_f32_e32 v22, 0x4f800000, v21
	v_cmp_gt_f32_e64 s[0:1], s61, v21
	v_cndmask_b32_e32 v19, v19, v24, vcc
	v_cmp_class_f32_e32 vcc, v20, v194
	v_cndmask_b32_e64 v21, v21, v22, s[0:1]
	v_sqrt_f32_e32 v22, v21
	v_cndmask_b32_e32 v19, v19, v20, vcc
	v_add_u32_e32 v20, -1, v22
	v_fma_f32 v24, -v20, v22, v21
	v_cmp_ge_f32_e32 vcc, 0, v24
	v_add_u32_e32 v24, 1, v22
	s_nop 0
	v_cndmask_b32_e32 v20, v22, v20, vcc
	v_fma_f32 v22, -v24, v22, v21
	v_cmp_lt_f32_e32 vcc, 0, v22
	s_nop 1
	v_cndmask_b32_e32 v20, v20, v24, vcc
	v_div_scale_f32 v24, s[8:9], v18, v18, 1.0
	v_rcp_f32_e32 v25, v24
	v_mul_f32_e32 v22, 0x37800000, v20
	v_cndmask_b32_e64 v20, v20, v22, s[0:1]
	v_cmp_class_f32_e32 vcc, v21, v194
	s_nop 1
	v_cndmask_b32_e32 v20, v20, v21, vcc
	v_fma_f32 v21, -v24, v25, 1.0
	v_fmac_f32_e32 v25, v21, v25
	v_div_scale_f32 v21, vcc, 1.0, v18, 1.0
	v_mul_f32_e32 v22, v21, v25
	v_fma_f32 v26, -v24, v22, v21
	v_fmac_f32_e32 v22, v26, v25
	v_fma_f32 v21, -v24, v22, v21
	v_div_scale_f32 v24, s[0:1], v15, v15, 1.0
	v_rcp_f32_e32 v26, v24
	v_div_fmas_f32 v21, v21, v25, v22
	v_div_fixup_f32 v25, v21, v18, 1.0
	v_fma_f32 v18, -v24, v26, 1.0
	v_fmac_f32_e32 v26, v18, v26
	v_div_scale_f32 v18, vcc, 1.0, v15, 1.0
	v_mul_f32_e32 v21, v18, v26
	v_fma_f32 v22, -v24, v21, v18
	v_fmac_f32_e32 v21, v22, v26
	v_div_scale_f32 v22, s[0:1], v20, v20, 1.0
	v_rcp_f32_e32 v27, v22
	v_fma_f32 v18, -v24, v21, v18
	v_div_fmas_f32 v18, v18, v26, v21
	v_div_fixup_f32 v24, v18, v15, 1.0
	v_fma_f32 v15, -v22, v27, 1.0
	v_fmac_f32_e32 v27, v15, v27
	v_div_scale_f32 v15, vcc, 1.0, v20, 1.0
	v_mul_f32_e32 v18, v15, v27
	v_fma_f32 v21, -v22, v18, v15
	v_fmac_f32_e32 v18, v21, v27
	v_div_scale_f32 v21, s[0:1], v19, v19, 1.0
	v_fma_f32 v15, -v22, v18, v15
	v_rcp_f32_e32 v22, v21
	v_div_fmas_f32 v15, v15, v27, v18
	v_div_fixup_f32 v27, v15, v20, 1.0
	v_pk_mul_f32 v[8:9], v[8:9], v[24:25]
	v_fma_f32 v15, -v21, v22, 1.0
	v_fmac_f32_e32 v22, v15, v22
	v_div_scale_f32 v15, vcc, 1.0, v19, 1.0
	v_mul_f32_e32 v18, v15, v22
	v_fma_f32 v20, -v21, v18, v15
	v_fmac_f32_e32 v18, v20, v22
	v_fma_f32 v15, -v21, v18, v15
	v_div_fmas_f32 v15, v15, v22, v18
	v_div_fixup_f32 v26, v15, v19, 1.0
	v_pk_mul_f32 v[12:13], v[12:13], v[26:27]
	v_pk_mul_f32 v[6:7], v[6:7], v[24:25]
	s_waitcnt vmcnt(0)
; #define LAS __attribute__((address_space(3)))
; __device__ __forceinline__ unsigned f2bf(float f) { unsigned u = __builtin_bit_cast(unsigned, f); return (u + 0x7fffu + ((u >> 16) & 1u)) >> 16; }
; __device__ __forceinline__ void sgu_phase(const LArgs& a, LAS unsigned char* lds) {
;     ...
;             const float x0 = bf2f(pk & 0xffffu), x1 = bf2f(pk >> 16);
;             const float mean = wave_sum(x0 + x1) * (1.f / 128.f); const float d0 = x0 - mean, d1 = x1 - mean;
;             const float rstd = 1.f / sqrtf(wave_sum(d0 * d0 + d1 * d1) * (1.f / 128.f) + 1e-5f);
;             *(LAS bf16*)(VVt + (2 * lane) * ROWB + r * 2) = (bf16)f2bf(d0 * rstd * ng0 + nb0); *(LAS bf16*)(VVt + (2 * lane + 1) * ROWB + r * 2) = (bf16)f2bf(d1 * rstd * ng1 + nb1);
	v_pk_fma_f32 v[12:13], v[0:1], v[12:13], v[2:3] op_sel_hi:[0,1,0]
	v_bfe_u32 v18, v12, 16, 1
	v_bfe_u32 v15, v13, 16, 1
	v_add3_u32 v21, v12, v18, s72
	v_lshlrev_b32_e32 v12, 16, v23
	v_and_b32_e32 v24, 0xffff0000, v23
	v_pk_fma_f32 v[8:9], v[0:1], v[8:9], v[2:3] op_sel_hi:[0,1,0]
	v_add3_u32 v22, v13, v15, s72
	v_add_f32_e32 v15, v12, v24
	v_bfe_u32 v20, v9, 16, 1
	v_bfe_u32 v19, v8, 16, 1
	v_lshlrev_b32_e32 v13, 16, v28
	ds_swizzle_b32 v23, v15 offset:swizzle(SWAP,1)
	v_and_b32_e32 v25, 0xffff0000, v28
	v_add3_u32 v19, v8, v19, s72
	v_add3_u32 v20, v9, v20, s72
	v_pk_mul_f32 v[8:9], v[16:17], v[26:27]
	v_add_f32_e32 v26, v13, v25
	ds_swizzle_b32 v27, v26 offset:swizzle(SWAP,1)
	v_pk_fma_f32 v[6:7], v[0:1], v[6:7], v[2:3] op_sel:[1,0,1]
	s_waitcnt lgkmcnt(1)
	v_add_f32_e32 v23, v15, v23
	v_bfe_u32 v28, v6, 16, 1
	ds_swizzle_b32 v29, v23 offset:swizzle(SWAP,2)
	v_add3_u32 v15, v6, v28, s72
	s_waitcnt lgkmcnt(1)
	v_add_f32_e32 v6, v26, v27
	ds_swizzle_b32 v26, v6 offset:swizzle(SWAP,2)
	v_bfe_u32 v16, v7, 16, 1
	v_add3_u32 v16, v7, v16, s72
	s_waitcnt lgkmcnt(1)
	v_add_f32_e32 v7, v23, v29
	v_pk_fma_f32 v[8:9], v[0:1], v[8:9], v[2:3] op_sel:[1,0,1]
	ds_swizzle_b32 v23, v7 offset:swizzle(SWAP,4)
	v_bfe_u32 v17, v8, 16, 1
	s_waitcnt lgkmcnt(1)
	v_add_f32_e32 v6, v6, v26
	v_add3_u32 v17, v8, v17, s72
	ds_swizzle_b32 v8, v6 offset:swizzle(SWAP,4)
	v_bfe_u32 v18, v9, 16, 1
	s_waitcnt lgkmcnt(1)
	v_add_f32_e32 v7, v7, v23
	v_add3_u32 v18, v9, v18, s72
	ds_swizzle_b32 v9, v7 offset:swizzle(SWAP,8)
	s_waitcnt lgkmcnt(1)
	v_add_f32_e32 v6, v6, v8
	ds_swizzle_b32 v8, v6 offset:swizzle(SWAP,8)
	v_lshlrev_b32_e32 v26, 16, v10
	v_and_b32_e32 v10, 0xffff0000, v10
	s_waitcnt lgkmcnt(1)
	v_add_f32_e32 v7, v7, v9
	ds_swizzle_b32 v9, v7 offset:swizzle(SWAP,16)
	s_waitcnt lgkmcnt(1)
	v_add_f32_e32 v6, v6, v8
	ds_swizzle_b32 v8, v6 offset:swizzle(SWAP,16)
	v_lshlrev_b32_e32 v27, 16, v11
	v_and_b32_e32 v11, 0xffff0000, v11
	s_waitcnt lgkmcnt(1)
	v_add_f32_e32 v7, v7, v9
	v_add_f32_e32 v9, v27, v11
	v_readlane_b32 s0, v7, 0
	v_readlane_b32 s3, v7, 32
	v_add_f32_e32 v7, v26, v10
	s_waitcnt lgkmcnt(0)
	v_add_f32_e32 v6, v6, v8
	ds_swizzle_b32 v8, v7 offset:swizzle(SWAP,1)
	ds_swizzle_b32 v23, v9 offset:swizzle(SWAP,1)
	v_readlane_b32 s7, v6, 32
	v_readlane_b32 s1, v6, 0
	v_mov_b32_e32 v6, s3
	s_waitcnt lgkmcnt(1)
	v_add_f32_e32 v28, v7, v8
	v_mov_b32_e32 v7, s7
	v_pk_add_f32 v[6:7], s[0:1], v[6:7]
	s_waitcnt lgkmcnt(0)
	v_add_f32_e32 v23, v9, v23
	v_pk_fma_f32 v[8:9], v[6:7], s[12:13], v[12:13] op_sel_hi:[1,0,1] neg_lo:[1,0,0] neg_hi:[1,0,0]
	v_pk_fma_f32 v[6:7], v[6:7], s[12:13], v[24:25] op_sel_hi:[1,0,1] neg_lo:[1,0,0] neg_hi:[1,0,0]
	ds_swizzle_b32 v29, v28 offset:swizzle(SWAP,2)
	v_mul_f32_e32 v12, v6, v6
	v_fmac_f32_e32 v12, v8, v8
	ds_swizzle_b32 v13, v12 offset:swizzle(SWAP,1)
	ds_swizzle_b32 v30, v23 offset:swizzle(SWAP,2)
	s_waitcnt lgkmcnt(2)
	v_add_f32_e32 v24, v28, v29
	ds_swizzle_b32 v25, v24 offset:swizzle(SWAP,4)
	s_waitcnt lgkmcnt(2)
	v_add_f32_e32 v12, v12, v13
	ds_swizzle_b32 v13, v12 offset:swizzle(SWAP,2)
	s_waitcnt lgkmcnt(2)
	v_add_f32_e32 v23, v23, v30
	s_waitcnt lgkmcnt(1)
	v_add_f32_e32 v24, v24, v25
	ds_swizzle_b32 v28, v23 offset:swizzle(SWAP,4)
	ds_swizzle_b32 v25, v24 offset:swizzle(SWAP,8)
	s_waitcnt lgkmcnt(2)
	v_add_f32_e32 v12, v12, v13
	ds_swizzle_b32 v13, v12 offset:swizzle(SWAP,4)
	s_waitcnt lgkmcnt(2)
	v_add_f32_e32 v23, v23, v28
	s_waitcnt lgkmcnt(1)
	v_add_f32_e32 v24, v24, v25
	ds_swizzle_b32 v28, v23 offset:swizzle(SWAP,8)
	ds_swizzle_b32 v25, v24 offset:swizzle(SWAP,16)
	s_waitcnt lgkmcnt(2)
	v_add_f32_e32 v12, v12, v13
	ds_swizzle_b32 v13, v12 offset:swizzle(SWAP,8)
	s_waitcnt lgkmcnt(2)
	v_add_f32_e32 v23, v23, v28
	s_waitcnt lgkmcnt(1)
	v_add_f32_e32 v24, v24, v25
	ds_swizzle_b32 v28, v23 offset:swizzle(SWAP,16)
	v_readlane_b32 s0, v24, 0
	v_readlane_b32 s3, v24, 32
	s_waitcnt lgkmcnt(1)
	v_add_f32_e32 v24, v12, v13
	ds_swizzle_b32 v25, v24 offset:swizzle(SWAP,16)
	s_waitcnt lgkmcnt(1)
	v_add_f32_e32 v23, v23, v28
	v_mov_b32_e32 v12, s3
	v_readlane_b32 s1, v23, 0
	v_readlane_b32 s7, v23, 32
	s_waitcnt lgkmcnt(0)
	v_add_f32_e32 v23, v24, v25
	v_mul_f32_e32 v24, v7, v7
	v_fmac_f32_e32 v24, v9, v9
	ds_swizzle_b32 v25, v24 offset:swizzle(SWAP,1)
	v_mov_b32_e32 v13, s7
	v_readlane_b32 s7, v23, 32
	v_readlane_b32 s3, v23, 0
	s_waitcnt lgkmcnt(0)
	v_add_f32_e32 v24, v24, v25
	ds_swizzle_b32 v25, v24 offset:swizzle(SWAP,2)
	v_mov_b32_e32 v23, s7
	v_add_f32_e32 v23, s3, v23
	v_fmamk_f32 v23, v23, 0x3c000000, v197
	v_mul_f32_e32 v28, 0x4f800000, v23
	s_waitcnt lgkmcnt(0)
	v_add_f32_e32 v29, v24, v25
	ds_swizzle_b32 v30, v29 offset:swizzle(SWAP,4)
	v_pk_add_f32 v[24:25], s[0:1], v[12:13]
	v_cmp_gt_f32_e32 vcc, s61, v23
	v_pk_fma_f32 v[12:13], v[24:25], s[12:13], v[26:27] op_sel_hi:[1,0,1] neg_lo:[1,0,0] neg_hi:[1,0,0]
	v_pk_fma_f32 v[10:11], v[24:25], s[12:13], v[10:11] op_sel_hi:[1,0,1] neg_lo:[1,0,0] neg_hi:[1,0,0]
	s_waitcnt lgkmcnt(0)
	v_add_f32_e32 v25, v29, v30
	ds_swizzle_b32 v26, v25 offset:swizzle(SWAP,8)
	v_cndmask_b32_e32 v23, v23, v28, vcc
	v_sqrt_f32_e32 v28, v23
	s_waitcnt lgkmcnt(0)
	v_add_f32_e32 v25, v25, v26
	ds_swizzle_b32 v26, v25 offset:swizzle(SWAP,16)
	v_add_u32_e32 v24, -1, v28
	v_fma_f32 v27, -v24, v28, v23
	v_cmp_ge_f32_e64 s[0:1], 0, v27
	v_add_u32_e32 v27, 1, v28
	s_waitcnt lgkmcnt(0)
	v_add_f32_e32 v25, v25, v26
	v_mul_f32_e32 v26, v10, v10
	v_cndmask_b32_e64 v24, v28, v24, s[0:1]
	v_fma_f32 v28, -v27, v28, v23
	v_fmac_f32_e32 v26, v12, v12
	v_cmp_lt_f32_e64 s[0:1], 0, v28
	ds_swizzle_b32 v28, v26 offset:swizzle(SWAP,1)
	s_waitcnt lgkmcnt(0)
; #define LAS __attribute__((address_space(3)))
; __device__ __forceinline__ unsigned f2bf(float f) { unsigned u = __builtin_bit_cast(unsigned, f); return (u + 0x7fffu + ((u >> 16) & 1u)) >> 16; }
; __device__ __forceinline__ void sgu_phase(const LArgs& a, LAS unsigned char* lds) {
;     ...
;             const int r = wid * 16 + rr; const unsigned pk = *(const unsigned*)(Gg + (size_t)(row0 + r) * 1024 + g * 128 + 2 * lane);
;             const float x0 = bf2f(pk & 0xffffu), x1 = bf2f(pk >> 16);
;             const float mean = wave_sum(x0 + x1) * (1.f / 128.f); const float d0 = x0 - mean, d1 = x1 - mean;
;             const float rstd = 1.f / sqrtf(wave_sum(d0 * d0 + d1 * d1) * (1.f / 128.f) + 1e-5f);
;             *(LAS bf16*)(VVt + (2 * lane) * ROWB + r * 2) = (bf16)f2bf(d0 * rstd * ng0 + nb0); *(LAS bf16*)(VVt + (2 * lane + 1) * ROWB + r * 2) = (bf16)f2bf(d1 * rstd * ng1 + nb1);
	v_add_f32_e32 v26, v26, v28
	ds_swizzle_b32 v28, v26 offset:swizzle(SWAP,2)
	v_cndmask_b32_e64 v24, v24, v27, s[0:1]
	v_mul_f32_e32 v27, 0x37800000, v24
	v_readlane_b32 s1, v25, 32
	v_readlane_b32 s0, v25, 0
	s_waitcnt lgkmcnt(0)
	v_add_f32_e32 v26, v26, v28
	ds_swizzle_b32 v28, v26 offset:swizzle(SWAP,4)
	v_mov_b32_e32 v25, s1
	v_cndmask_b32_e32 v24, v24, v27, vcc
	v_add_f32_e32 v25, s0, v25
	v_fmamk_f32 v25, v25, 0x3c000000, v197
	s_waitcnt lgkmcnt(0)
	v_add_f32_e32 v26, v26, v28
	ds_swizzle_b32 v27, v26 offset:swizzle(SWAP,8)
	v_mul_f32_e32 v29, 0x4f800000, v25
	v_cmp_gt_f32_e64 s[0:1], s61, v25
	v_cmp_class_f32_e32 vcc, v23, v194
	s_waitcnt lgkmcnt(0)
	v_add_f32_e32 v26, v26, v27
	v_cndmask_b32_e64 v25, v25, v29, s[0:1]
	v_sqrt_f32_e32 v29, v25
	ds_swizzle_b32 v27, v26 offset:swizzle(SWAP,16)
	v_cndmask_b32_e32 v23, v24, v23, vcc
	v_add_u32_e32 v24, -1, v29
	v_fma_f32 v28, -v24, v29, v25
	v_cmp_ge_f32_e32 vcc, 0, v28
	v_add_u32_e32 v28, 1, v29
	s_waitcnt lgkmcnt(0)
	v_add_f32_e32 v26, v26, v27
	v_mul_f32_e32 v27, v11, v11
	v_cndmask_b32_e32 v24, v29, v24, vcc
	v_fma_f32 v29, -v28, v29, v25
	v_fmac_f32_e32 v27, v13, v13
	v_cmp_lt_f32_e32 vcc, 0, v29
	ds_swizzle_b32 v29, v27 offset:swizzle(SWAP,1)
	v_readlane_b32 s7, v26, 32
	v_cndmask_b32_e32 v24, v24, v28, vcc
	v_readlane_b32 s3, v26, 0
	v_mov_b32_e32 v26, s7
	s_waitcnt lgkmcnt(0)
	v_add_f32_e32 v27, v27, v29
	ds_swizzle_b32 v29, v27 offset:swizzle(SWAP,2)
	v_mul_f32_e32 v28, 0x37800000, v24
	v_add_f32_e32 v26, s3, v26
	v_fmamk_f32 v26, v26, 0x3c000000, v197
	v_cndmask_b32_e64 v24, v24, v28, s[0:1]
	s_waitcnt lgkmcnt(0)
	v_add_f32_e32 v27, v27, v29
	ds_swizzle_b32 v29, v27 offset:swizzle(SWAP,4)
	v_mul_f32_e32 v30, 0x4f800000, v26
	v_cmp_gt_f32_e32 vcc, s61, v26
	v_cmp_class_f32_e64 s[0:1], v25, v194
	s_waitcnt lgkmcnt(0)
	v_add_f32_e32 v27, v27, v29
	ds_swizzle_b32 v28, v27 offset:swizzle(SWAP,8)
	v_cndmask_b32_e32 v26, v26, v30, vcc
	v_sqrt_f32_e32 v30, v26
	v_cndmask_b32_e64 v24, v24, v25, s[0:1]
	s_waitcnt lgkmcnt(0)
	v_add_f32_e32 v27, v27, v28
	ds_swizzle_b32 v28, v27 offset:swizzle(SWAP,16)
	v_add_u32_e32 v25, -1, v30
	v_fma_f32 v29, -v25, v30, v26
	v_cmp_ge_f32_e64 s[0:1], 0, v29
	v_add_u32_e32 v29, 1, v30
	s_waitcnt lgkmcnt(0)
	v_add_f32_e32 v27, v27, v28
	v_cndmask_b32_e64 v25, v30, v25, s[0:1]
	v_fma_f32 v30, -v29, v30, v26
	v_cmp_lt_f32_e64 s[0:1], 0, v30
	s_nop 1
	v_cndmask_b32_e64 v25, v25, v29, s[0:1]
	v_readlane_b32 s1, v27, 32
	v_readlane_b32 s0, v27, 0
	v_mul_f32_e32 v29, 0x37800000, v25
	v_mov_b32_e32 v27, s1
	v_add_f32_e32 v27, s0, v27
	v_fmamk_f32 v27, v27, 0x3c000000, v197
	v_mul_f32_e32 v28, 0x4f800000, v27
	v_cmp_gt_f32_e64 s[0:1], s61, v27
	v_cndmask_b32_e32 v25, v25, v29, vcc
	v_cmp_class_f32_e32 vcc, v26, v194
	v_cndmask_b32_e64 v27, v27, v28, s[0:1]
	v_sqrt_f32_e32 v28, v27
	v_cndmask_b32_e32 v32, v25, v26, vcc
	v_add_u32_e32 v25, -1, v28
	v_fma_f32 v26, -v25, v28, v27
	v_cmp_ge_f32_e32 vcc, 0, v26
	v_add_u32_e32 v26, 1, v28
	s_nop 0
	v_cndmask_b32_e32 v25, v28, v25, vcc
	v_fma_f32 v28, -v26, v28, v27
	v_cmp_lt_f32_e32 vcc, 0, v28
	v_div_scale_f32 v28, s[8:9], v24, v24, 1.0
	v_rcp_f32_e32 v29, v28
	v_cndmask_b32_e32 v25, v25, v26, vcc
	v_mul_f32_e32 v26, 0x37800000, v25
	v_cndmask_b32_e64 v25, v25, v26, s[0:1]
	v_cmp_class_f32_e32 vcc, v27, v194
	s_nop 1
	v_cndmask_b32_e32 v30, v25, v27, vcc
	v_fma_f32 v25, -v28, v29, 1.0
	v_fmac_f32_e32 v29, v25, v29
	v_div_scale_f32 v25, vcc, 1.0, v24, 1.0
	v_mul_f32_e32 v26, v25, v29
	v_fma_f32 v27, -v28, v26, v25
	v_fmac_f32_e32 v26, v27, v29
	v_fma_f32 v25, -v28, v26, v25
	v_div_scale_f32 v28, s[0:1], v23, v23, 1.0
	v_rcp_f32_e32 v31, v28
	v_div_fmas_f32 v25, v25, v29, v26
	v_div_fixup_f32 v27, v25, v24, 1.0
	v_div_scale_f32 v33, s[0:1], v30, v30, 1.0
	v_fma_f32 v24, -v28, v31, 1.0
	v_fmac_f32_e32 v31, v24, v31
	v_div_scale_f32 v24, vcc, 1.0, v23, 1.0
	v_mul_f32_e32 v25, v24, v31
	v_fma_f32 v26, -v28, v25, v24
	v_fmac_f32_e32 v25, v26, v31
	v_fma_f32 v24, -v28, v25, v24
	v_div_fmas_f32 v24, v24, v31, v25
	v_div_fixup_f32 v26, v24, v23, 1.0
	v_add_u32_e32 v24, s5, v53
	v_ashrrev_i32_e32 v25, 31, v24
	v_add_u32_e32 v28, s5, v54
	v_lshlrev_b64 v[24:25], 11, v[24:25]
	v_ashrrev_i32_e32 v29, 31, v28
	v_lshl_add_u64 v[24:25], v[4:5], 0, v[24:25]
	v_lshlrev_b64 v[28:29], 11, v[28:29]
	v_lshl_add_u64 v[28:29], v[4:5], 0, v[28:29]
	global_load_dword v35, v[24:25], off
	global_load_dword v75, v[28:29], off
	v_rcp_f32_e32 v34, v33
	v_div_scale_f32 v28, s[0:1], v32, v32, 1.0
	v_pk_mul_f32 v[8:9], v[8:9], v[26:27]
	v_fma_f32 v23, -v33, v34, 1.0
	v_fmac_f32_e32 v34, v23, v34
	v_div_scale_f32 v23, vcc, 1.0, v30, 1.0
	v_mul_f32_e32 v31, v23, v34
	v_fma_f32 v24, -v33, v31, v23
	v_fmac_f32_e32 v31, v24, v34
	v_fma_f32 v23, -v33, v31, v23
	v_div_fmas_f32 v23, v23, v34, v31
	v_div_fixup_f32 v29, v23, v30, 1.0
	v_add_u32_e32 v24, s5, v55
	v_add_u32_e32 v30, s5, v56
	v_ashrrev_i32_e32 v25, 31, v24
	v_ashrrev_i32_e32 v31, 31, v30
	v_lshlrev_b64 v[24:25], 11, v[24:25]
	v_lshlrev_b64 v[30:31], 11, v[30:31]
	v_lshl_add_u64 v[24:25], v[4:5], 0, v[24:25]
	v_lshl_add_u64 v[30:31], v[4:5], 0, v[30:31]
	global_load_dword v34, v[24:25], off
	s_nop 0
	global_load_dword v30, v[30:31], off
	v_rcp_f32_e32 v33, v28
	v_pk_fma_f32 v[8:9], v[0:1], v[8:9], v[2:3] op_sel_hi:[0,1,0]
	v_bfe_u32 v31, v8, 16, 1
	v_add3_u32 v8, v8, v31, s72
	v_fma_f32 v23, -v28, v33, 1.0
	v_fmac_f32_e32 v33, v23, v33
	v_div_scale_f32 v23, vcc, 1.0, v32, 1.0
	v_mul_f32_e32 v24, v23, v33
	v_fma_f32 v25, -v28, v24, v23
	v_fmac_f32_e32 v24, v25, v33
	v_fma_f32 v23, -v28, v24, v23
	v_div_fmas_f32 v23, v23, v33, v24
	v_div_fixup_f32 v28, v23, v32, 1.0
	v_pk_mul_f32 v[12:13], v[12:13], v[28:29]
; #define LAS __attribute__((address_space(3)))
; __device__ __forceinline__ unsigned f2bf(float f) { unsigned u = __builtin_bit_cast(unsigned, f); return (u + 0x7fffu + ((u >> 16) & 1u)) >> 16; }
; __device__ __forceinline__ void sgu_phase(const LArgs& a, LAS unsigned char* lds) {
;     ...
;             const int r = wid * 16 + rr; const unsigned pk = *(const unsigned*)(Gg + (size_t)(row0 + r) * 1024 + g * 128 + 2 * lane);
;             const float x0 = bf2f(pk & 0xffffu), x1 = bf2f(pk >> 16);
;             const float mean = wave_sum(x0 + x1) * (1.f / 128.f); const float d0 = x0 - mean, d1 = x1 - mean;
;             const float rstd = 1.f / sqrtf(wave_sum(d0 * d0 + d1 * d1) * (1.f / 128.f) + 1e-5f);
;             *(LAS bf16*)(VVt + (2 * lane) * ROWB + r * 2) = (bf16)f2bf(d0 * rstd * ng0 + nb0); *(LAS bf16*)(VVt + (2 * lane + 1) * ROWB + r * 2) = (bf16)f2bf(d1 * rstd * ng1 + nb1);
	v_bfe_u32 v25, v9, 16, 1
	v_pk_fma_f32 v[12:13], v[0:1], v[12:13], v[2:3] op_sel_hi:[0,1,0]
	v_bfe_u32 v24, v12, 16, 1
	v_add3_u32 v9, v9, v25, s72
	v_bfe_u32 v23, v13, 16, 1
	v_add3_u32 v12, v12, v24, s72
	v_perm_b32 v24, v9, v8, s10
	v_pk_mul_f32 v[8:9], v[10:11], v[28:29]
	v_pk_mul_f32 v[6:7], v[6:7], v[26:27]
	v_add3_u32 v13, v13, v23, s72
	v_pk_fma_f32 v[6:7], v[0:1], v[6:7], v[2:3] op_sel:[1,0,1]
	v_pk_fma_f32 v[8:9], v[0:1], v[8:9], v[2:3] op_sel:[1,0,1]
	v_perm_b32 v25, v13, v12, s10
	v_perm_b32 v23, v22, v21, s10
	v_perm_b32 v22, v20, v19, s10
	v_bfe_u32 v10, v9, 16, 1
	v_bfe_u32 v11, v8, 16, 1
	v_bfe_u32 v13, v6, 16, 1
	ds_write_b128 v71, v[22:25] offset:34816
	v_bfe_u32 v12, v7, 16, 1
	v_add3_u32 v19, v6, v13, s72
	v_add3_u32 v21, v8, v11, s72
	v_add3_u32 v22, v9, v10, s72
	v_add_u32_e32 v6, s5, v57
	v_add_u32_e32 v8, s5, v58
	v_add_u32_e32 v10, s5, v59
	v_add3_u32 v20, v7, v12, s72
	v_ashrrev_i32_e32 v7, 31, v6
	v_ashrrev_i32_e32 v9, 31, v8
	v_ashrrev_i32_e32 v11, 31, v10
	v_add_u32_e32 v12, s5, v60
	v_lshlrev_b64 v[6:7], 11, v[6:7]
	v_lshlrev_b64 v[8:9], 11, v[8:9]
	v_lshlrev_b64 v[10:11], 11, v[10:11]
	v_ashrrev_i32_e32 v13, 31, v12
	v_lshl_add_u64 v[6:7], v[4:5], 0, v[6:7]
	v_lshl_add_u64 v[8:9], v[4:5], 0, v[8:9]
	v_lshl_add_u64 v[10:11], v[4:5], 0, v[10:11]
	v_lshlrev_b64 v[12:13], 11, v[12:13]
	v_lshl_add_u64 v[4:5], v[4:5], 0, v[12:13]
	global_load_dword v23, v[6:7], off
	global_load_dword v24, v[8:9], off
	global_load_dword v25, v[10:11], off
	global_load_dword v26, v[4:5], off
	s_waitcnt vmcnt(6)
	v_lshlrev_b32_e32 v9, 16, v75
	v_lshlrev_b32_e32 v8, 16, v35
	v_and_b32_e32 v10, 0xffff0000, v35
	v_and_b32_e32 v11, 0xffff0000, v75
	v_add_f32_e32 v4, v8, v10
	v_add_f32_e32 v12, v9, v11
	ds_swizzle_b32 v5, v4 offset:swizzle(SWAP,1)
	ds_swizzle_b32 v13, v12 offset:swizzle(SWAP,1)
	v_perm_b32 v7, v22, v21, s10
	v_perm_b32 v6, v20, v19, s10
	v_or_b32_e32 v75, s6, v61
	s_waitcnt lgkmcnt(1)
	v_add_f32_e32 v4, v4, v5
	s_waitcnt lgkmcnt(0)
	v_add_f32_e32 v12, v12, v13
	ds_swizzle_b32 v21, v4 offset:swizzle(SWAP,2)
	ds_swizzle_b32 v13, v12 offset:swizzle(SWAP,2)
	v_perm_b32 v5, v18, v17, s10
	v_lshlrev_b32_e32 v75, 2, v75
	s_waitcnt lgkmcnt(1)
	v_add_f32_e32 v17, v4, v21
	s_waitcnt lgkmcnt(0)
	v_add_f32_e32 v12, v12, v13
	ds_swizzle_b32 v18, v17 offset:swizzle(SWAP,4)
	ds_swizzle_b32 v13, v12 offset:swizzle(SWAP,4)
	v_perm_b32 v4, v16, v15, s10
	ds_write_b128 v71, v[4:7] offset:35088
	s_waitcnt vmcnt(5)
	v_lshlrev_b32_e32 v4, 16, v34
	s_waitcnt lgkmcnt(2)
	v_add_f32_e32 v6, v17, v18
	s_waitcnt lgkmcnt(1)
	v_add_f32_e32 v12, v12, v13
	ds_swizzle_b32 v7, v6 offset:swizzle(SWAP,8)
	ds_swizzle_b32 v13, v12 offset:swizzle(SWAP,8)
	s_waitcnt vmcnt(4)
	v_lshlrev_b32_e32 v5, 16, v30
	s_waitcnt lgkmcnt(1)
	v_add_f32_e32 v15, v6, v7
	s_waitcnt lgkmcnt(0)
	v_add_f32_e32 v12, v12, v13
	ds_swizzle_b32 v16, v15 offset:swizzle(SWAP,16)
	ds_swizzle_b32 v13, v12 offset:swizzle(SWAP,16)
	v_and_b32_e32 v6, 0xffff0000, v34
	v_and_b32_e32 v7, 0xffff0000, v30
	s_waitcnt lgkmcnt(1)
	v_add_f32_e32 v15, v15, v16
	s_waitcnt lgkmcnt(0)
	v_add_f32_e32 v12, v12, v13
	v_add_f32_e32 v13, v4, v6
	v_readlane_b32 s0, v15, 0
	v_readlane_b32 s3, v15, 32
	ds_swizzle_b32 v15, v13 offset:swizzle(SWAP,1)
	v_add_f32_e32 v16, v5, v7
	ds_swizzle_b32 v17, v16 offset:swizzle(SWAP,1)
	v_readlane_b32 s7, v12, 32
	v_readlane_b32 s1, v12, 0
	s_waitcnt lgkmcnt(1)
	v_add_f32_e32 v15, v13, v15
	v_mov_b32_e32 v12, s3
	v_mov_b32_e32 v13, s7
	v_pk_add_f32 v[12:13], s[0:1], v[12:13]
	ds_swizzle_b32 v18, v15 offset:swizzle(SWAP,2)
	v_pk_fma_f32 v[10:11], v[12:13], s[12:13], v[10:11] op_sel_hi:[1,0,1] neg_lo:[1,0,0] neg_hi:[1,0,0]
	v_pk_fma_f32 v[8:9], v[12:13], s[12:13], v[8:9] op_sel_hi:[1,0,1] neg_lo:[1,0,0] neg_hi:[1,0,0]
	v_mul_f32_e32 v12, v10, v10
	s_waitcnt lgkmcnt(1)
	v_add_f32_e32 v16, v16, v17
	v_fmac_f32_e32 v12, v8, v8
	ds_swizzle_b32 v17, v16 offset:swizzle(SWAP,2)
	ds_swizzle_b32 v13, v12 offset:swizzle(SWAP,1)
	s_waitcnt lgkmcnt(2)
	v_add_f32_e32 v15, v15, v18
	ds_swizzle_b32 v18, v15 offset:swizzle(SWAP,4)
	s_waitcnt lgkmcnt(2)
	v_add_f32_e32 v16, v16, v17
	s_waitcnt lgkmcnt(1)
	v_add_f32_e32 v12, v12, v13
	ds_swizzle_b32 v17, v16 offset:swizzle(SWAP,4)
	ds_swizzle_b32 v13, v12 offset:swizzle(SWAP,2)
	s_waitcnt lgkmcnt(2)
	v_add_f32_e32 v15, v15, v18
	ds_swizzle_b32 v18, v15 offset:swizzle(SWAP,8)
	s_waitcnt lgkmcnt(2)
	v_add_f32_e32 v16, v16, v17
	s_waitcnt lgkmcnt(1)
	v_add_f32_e32 v12, v12, v13
	ds_swizzle_b32 v17, v16 offset:swizzle(SWAP,8)
	ds_swizzle_b32 v13, v12 offset:swizzle(SWAP,4)
	s_waitcnt lgkmcnt(2)
	v_add_f32_e32 v15, v15, v18
	ds_swizzle_b32 v18, v15 offset:swizzle(SWAP,16)
	s_waitcnt lgkmcnt(2)
	v_add_f32_e32 v16, v16, v17
	s_waitcnt lgkmcnt(1)
	v_add_f32_e32 v12, v12, v13
	ds_swizzle_b32 v17, v16 offset:swizzle(SWAP,16)
	ds_swizzle_b32 v13, v12 offset:swizzle(SWAP,8)
	s_waitcnt lgkmcnt(2)
	v_add_f32_e32 v15, v15, v18
	s_nop 0
	v_readlane_b32 s0, v15, 0
	v_readlane_b32 s3, v15, 32
	s_waitcnt lgkmcnt(1)
	v_add_f32_e32 v15, v16, v17
	s_waitcnt lgkmcnt(0)
	v_add_f32_e32 v16, v12, v13
	ds_swizzle_b32 v17, v16 offset:swizzle(SWAP,16)
	v_readlane_b32 s1, v15, 0
	v_readlane_b32 s7, v15, 32
	v_mov_b32_e32 v12, s3
	s_waitcnt lgkmcnt(0)
	v_add_f32_e32 v15, v16, v17
	v_mul_f32_e32 v16, v11, v11
	v_fmac_f32_e32 v16, v9, v9
	ds_swizzle_b32 v17, v16 offset:swizzle(SWAP,1)
	v_mov_b32_e32 v13, s7
	v_pk_add_f32 v[12:13], s[0:1], v[12:13]
	v_readlane_b32 s7, v15, 32
	v_pk_fma_f32 v[4:5], v[12:13], s[12:13], v[4:5] op_sel_hi:[1,0,1] neg_lo:[1,0,0] neg_hi:[1,0,0]
	s_waitcnt lgkmcnt(0)
; #define LAS __attribute__((address_space(3)))
; __device__ __forceinline__ unsigned f2bf(float f) { unsigned u = __builtin_bit_cast(unsigned, f); return (u + 0x7fffu + ((u >> 16) & 1u)) >> 16; }
; __device__ __forceinline__ void sgu_phase(const LArgs& a, LAS unsigned char* lds) {
;     ...
; #pragma unroll
;         for (int rr = 0; rr < 16; ++rr) {
;             const int r = wid * 16 + rr; const unsigned pk = *(const unsigned*)(Gg + (size_t)(row0 + r) * 1024 + g * 128 + 2 * lane);
;             const float x0 = bf2f(pk & 0xffffu), x1 = bf2f(pk >> 16);
;             const float mean = wave_sum(x0 + x1) * (1.f / 128.f); const float d0 = x0 - mean, d1 = x1 - mean;
;             const float rstd = 1.f / sqrtf(wave_sum(d0 * d0 + d1 * d1) * (1.f / 128.f) + 1e-5f);
;             *(LAS bf16*)(VVt + (2 * lane) * ROWB + r * 2) = (bf16)f2bf(d0 * rstd * ng0 + nb0); *(LAS bf16*)(VVt + (2 * lane + 1) * ROWB + r * 2) = (bf16)f2bf(d1 * rstd * ng1 + nb1);
;         }
	v_add_f32_e32 v16, v16, v17
	ds_swizzle_b32 v17, v16 offset:swizzle(SWAP,2)
	v_pk_fma_f32 v[6:7], v[12:13], s[12:13], v[6:7] op_sel_hi:[1,0,1] neg_lo:[1,0,0] neg_hi:[1,0,0]
	v_readlane_b32 s3, v15, 0
	v_mov_b32_e32 v15, s7
	s_waitcnt lgkmcnt(0)
	v_add_f32_e32 v16, v16, v17
	ds_swizzle_b32 v17, v16 offset:swizzle(SWAP,4)
	v_add_f32_e32 v15, s3, v15
	v_fmamk_f32 v15, v15, 0x3c000000, v197
	v_mul_f32_e32 v18, 0x4f800000, v15
	v_cmp_gt_f32_e32 vcc, s61, v15
	s_waitcnt lgkmcnt(0)
	v_add_f32_e32 v13, v16, v17
	ds_swizzle_b32 v16, v13 offset:swizzle(SWAP,8)
	v_cndmask_b32_e32 v15, v15, v18, vcc
	v_sqrt_f32_e32 v18, v15
	s_waitcnt lgkmcnt(0)
	v_add_f32_e32 v13, v13, v16
	ds_swizzle_b32 v16, v13 offset:swizzle(SWAP,16)
	v_add_u32_e32 v12, -1, v18
	v_fma_f32 v17, -v12, v18, v15
	v_cmp_ge_f32_e64 s[0:1], 0, v17
	v_add_u32_e32 v17, 1, v18
	s_waitcnt lgkmcnt(0)
	v_add_f32_e32 v13, v13, v16
	v_mul_f32_e32 v16, v6, v6
	v_cndmask_b32_e64 v12, v18, v12, s[0:1]
	v_fma_f32 v18, -v17, v18, v15
	v_fmac_f32_e32 v16, v4, v4
	v_cmp_lt_f32_e64 s[0:1], 0, v18
	ds_swizzle_b32 v18, v16 offset:swizzle(SWAP,1)
	s_waitcnt lgkmcnt(0)
	v_add_f32_e32 v16, v16, v18
	ds_swizzle_b32 v18, v16 offset:swizzle(SWAP,2)
	v_cndmask_b32_e64 v12, v12, v17, s[0:1]
	v_mul_f32_e32 v17, 0x37800000, v12
	v_readlane_b32 s1, v13, 32
	v_readlane_b32 s0, v13, 0
	s_waitcnt lgkmcnt(0)
	v_add_f32_e32 v16, v16, v18
	ds_swizzle_b32 v18, v16 offset:swizzle(SWAP,4)
	v_mov_b32_e32 v13, s1
	v_cndmask_b32_e32 v12, v12, v17, vcc
	v_add_f32_e32 v13, s0, v13
	v_fmamk_f32 v13, v13, 0x3c000000, v197
	s_waitcnt lgkmcnt(0)
	v_add_f32_e32 v16, v16, v18
	ds_swizzle_b32 v17, v16 offset:swizzle(SWAP,8)
	v_mul_f32_e32 v19, 0x4f800000, v13
	v_cmp_gt_f32_e64 s[0:1], s61, v13
	v_cmp_class_f32_e32 vcc, v15, v194
	s_waitcnt lgkmcnt(0)
	v_add_f32_e32 v16, v16, v17
	v_cndmask_b32_e64 v13, v13, v19, s[0:1]
	v_sqrt_f32_e32 v19, v13
	ds_swizzle_b32 v17, v16 offset:swizzle(SWAP,16)
	v_cndmask_b32_e32 v12, v12, v15, vcc
	v_add_u32_e32 v15, -1, v19
	v_fma_f32 v18, -v15, v19, v13
	v_cmp_ge_f32_e32 vcc, 0, v18
	v_add_u32_e32 v18, 1, v19
	s_waitcnt lgkmcnt(0)
	v_add_f32_e32 v16, v16, v17
	v_mul_f32_e32 v17, v7, v7
	v_cndmask_b32_e32 v15, v19, v15, vcc
	v_fma_f32 v19, -v18, v19, v13
	v_fmac_f32_e32 v17, v5, v5
	v_cmp_lt_f32_e32 vcc, 0, v19
	ds_swizzle_b32 v19, v17 offset:swizzle(SWAP,1)
	v_readlane_b32 s7, v16, 32
	v_cndmask_b32_e32 v15, v15, v18, vcc
	v_readlane_b32 s3, v16, 0
	v_mov_b32_e32 v16, s7
	s_waitcnt lgkmcnt(0)
	v_add_f32_e32 v17, v17, v19
	ds_swizzle_b32 v19, v17 offset:swizzle(SWAP,2)
	v_mul_f32_e32 v18, 0x37800000, v15
	v_add_f32_e32 v16, s3, v16
	v_fmamk_f32 v16, v16, 0x3c000000, v197
	v_cndmask_b32_e64 v15, v15, v18, s[0:1]
	s_waitcnt lgkmcnt(0)
	v_add_f32_e32 v17, v17, v19
	ds_swizzle_b32 v19, v17 offset:swizzle(SWAP,4)
	v_mul_f32_e32 v20, 0x4f800000, v16
	v_cmp_gt_f32_e32 vcc, s61, v16
	v_cmp_class_f32_e64 s[0:1], v13, v194
	s_waitcnt lgkmcnt(0)
	v_add_f32_e32 v17, v17, v19
	ds_swizzle_b32 v18, v17 offset:swizzle(SWAP,8)
	v_cndmask_b32_e32 v16, v16, v20, vcc
	v_sqrt_f32_e32 v20, v16
	v_cndmask_b32_e64 v13, v15, v13, s[0:1]
	s_waitcnt lgkmcnt(0)
	v_add_f32_e32 v17, v17, v18
	ds_swizzle_b32 v18, v17 offset:swizzle(SWAP,16)
	v_add_u32_e32 v15, -1, v20
	v_fma_f32 v19, -v15, v20, v16
	v_cmp_ge_f32_e64 s[0:1], 0, v19
	v_add_u32_e32 v19, 1, v20
	s_waitcnt lgkmcnt(0)
	v_add_f32_e32 v17, v17, v18
	v_cndmask_b32_e64 v15, v20, v15, s[0:1]
	v_fma_f32 v20, -v19, v20, v16
	v_cmp_lt_f32_e64 s[0:1], 0, v20
	s_nop 1
	v_cndmask_b32_e64 v15, v15, v19, s[0:1]
	v_readlane_b32 s1, v17, 32
	v_readlane_b32 s0, v17, 0
	v_mul_f32_e32 v19, 0x37800000, v15
	v_mov_b32_e32 v17, s1
	v_add_f32_e32 v17, s0, v17
	v_fmamk_f32 v17, v17, 0x3c000000, v197
	v_mul_f32_e32 v18, 0x4f800000, v17
	v_cmp_gt_f32_e64 s[0:1], s61, v17
	v_cndmask_b32_e32 v15, v15, v19, vcc
	v_cmp_class_f32_e32 vcc, v16, v194
	v_cndmask_b32_e64 v17, v17, v18, s[0:1]
	v_sqrt_f32_e32 v18, v17
	v_cndmask_b32_e32 v15, v15, v16, vcc
	v_add_u32_e32 v16, -1, v18
	v_fma_f32 v19, -v16, v18, v17
	v_cmp_ge_f32_e32 vcc, 0, v19
	v_add_u32_e32 v19, 1, v18
	s_nop 0
	v_cndmask_b32_e32 v16, v18, v16, vcc
	v_fma_f32 v18, -v19, v18, v17
	v_cmp_lt_f32_e32 vcc, 0, v18
	s_nop 1
	v_cndmask_b32_e32 v16, v16, v19, vcc
	v_div_scale_f32 v19, s[8:9], v13, v13, 1.0
	v_rcp_f32_e32 v20, v19
	v_mul_f32_e32 v18, 0x37800000, v16
	v_cndmask_b32_e64 v16, v16, v18, s[0:1]
	v_cmp_class_f32_e32 vcc, v17, v194
	s_nop 1
	v_cndmask_b32_e32 v16, v16, v17, vcc
	v_fma_f32 v17, -v19, v20, 1.0
	v_fmac_f32_e32 v20, v17, v20
	v_div_scale_f32 v17, vcc, 1.0, v13, 1.0
	v_mul_f32_e32 v18, v17, v20
	v_fma_f32 v21, -v19, v18, v17
	v_fmac_f32_e32 v18, v21, v20
	v_fma_f32 v17, -v19, v18, v17
	v_div_scale_f32 v19, s[0:1], v12, v12, 1.0
	v_rcp_f32_e32 v21, v19
	v_div_fmas_f32 v17, v17, v20, v18
	v_div_fixup_f32 v13, v17, v13, 1.0
	v_fma_f32 v17, -v19, v21, 1.0
	v_fmac_f32_e32 v21, v17, v21
	v_div_scale_f32 v17, vcc, 1.0, v12, 1.0
	v_mul_f32_e32 v18, v17, v21
	v_fma_f32 v20, -v19, v18, v17
	v_fmac_f32_e32 v18, v20, v21
	v_fma_f32 v17, -v19, v18, v17
	v_div_scale_f32 v19, s[0:1], v16, v16, 1.0
	v_rcp_f32_e32 v20, v19
	v_div_fmas_f32 v17, v17, v21, v18
	v_div_fixup_f32 v12, v17, v12, 1.0
	v_pk_mul_f32 v[8:9], v[8:9], v[12:13]
	v_fma_f32 v17, -v19, v20, 1.0
	v_fmac_f32_e32 v20, v17, v20
	v_div_scale_f32 v17, vcc, 1.0, v16, 1.0
	v_mul_f32_e32 v18, v17, v20
	v_fma_f32 v21, -v19, v18, v17
	v_fmac_f32_e32 v18, v21, v20
	v_fma_f32 v17, -v19, v18, v17
	v_div_scale_f32 v19, s[0:1], v15, v15, 1.0
	v_rcp_f32_e32 v21, v19
	v_div_fmas_f32 v17, v17, v20, v18
	v_div_fixup_f32 v17, v17, v16, 1.0
	v_pk_fma_f32 v[8:9], v[0:1], v[8:9], v[2:3] op_sel_hi:[0,1,0]
	v_fma_f32 v16, -v19, v21, 1.0
	v_fmac_f32_e32 v21, v16, v21
	v_div_scale_f32 v16, vcc, 1.0, v15, 1.0
	v_mul_f32_e32 v18, v16, v21
	v_fma_f32 v20, -v19, v18, v16
	v_fmac_f32_e32 v18, v20, v21
	v_fma_f32 v16, -v19, v18, v16
	v_div_fmas_f32 v16, v16, v21, v18
	v_div_fixup_f32 v16, v16, v15, 1.0
	v_pk_mul_f32 v[4:5], v[4:5], v[16:17]
	v_bfe_u32 v20, v8, 16, 1
	v_pk_fma_f32 v[4:5], v[0:1], v[4:5], v[2:3] op_sel_hi:[0,1,0]
	v_bfe_u32 v15, v5, 16, 1
	v_bfe_u32 v18, v4, 16, 1
	v_add3_u32 v20, v8, v20, s72
	v_add3_u32 v22, v4, v18, s72
	v_add3_u32 v15, v5, v15, s72
	v_pk_mul_f32 v[4:5], v[6:7], v[16:17]
	v_pk_mul_f32 v[6:7], v[10:11], v[12:13]
	s_waitcnt vmcnt(3)
; #define LAS __attribute__((address_space(3)))
; __device__ __forceinline__ unsigned f2bf(float f) { unsigned u = __builtin_bit_cast(unsigned, f); return (u + 0x7fffu + ((u >> 16) & 1u)) >> 16; }
; __device__ __forceinline__ void sgu_phase(const LArgs& a, LAS unsigned char* lds) {
;     ...
; #pragma unroll
;         for (int rr = 0; rr < 16; ++rr) {
;             const int r = wid * 16 + rr; const unsigned pk = *(const unsigned*)(Gg + (size_t)(row0 + r) * 1024 + g * 128 + 2 * lane);
;             const float x0 = bf2f(pk & 0xffffu), x1 = bf2f(pk >> 16);
;             const float mean = wave_sum(x0 + x1) * (1.f / 128.f); const float d0 = x0 - mean, d1 = x1 - mean;
;             const float rstd = 1.f / sqrtf(wave_sum(d0 * d0 + d1 * d1) * (1.f / 128.f) + 1e-5f);
;             *(LAS bf16*)(VVt + (2 * lane) * ROWB + r * 2) = (bf16)f2bf(d0 * rstd * ng0 + nb0); *(LAS bf16*)(VVt + (2 * lane + 1) * ROWB + r * 2) = (bf16)f2bf(d1 * rstd * ng1 + nb1);
;         }
	v_lshlrev_b32_e32 v8, 16, v23
	v_and_b32_e32 v10, 0xffff0000, v23
	v_bfe_u32 v19, v9, 16, 1
	v_add_f32_e32 v17, v8, v10
	v_add3_u32 v21, v9, v19, s72
	s_waitcnt vmcnt(2)
	v_lshlrev_b32_e32 v9, 16, v24
	ds_swizzle_b32 v18, v17 offset:swizzle(SWAP,1)
	v_and_b32_e32 v11, 0xffff0000, v24
	v_add_f32_e32 v19, v9, v11
	ds_swizzle_b32 v23, v19 offset:swizzle(SWAP,1)
	v_pk_fma_f32 v[6:7], v[0:1], v[6:7], v[2:3] op_sel:[1,0,1]
	s_waitcnt lgkmcnt(1)
	v_add_f32_e32 v17, v17, v18
	v_bfe_u32 v24, v6, 16, 1
	ds_swizzle_b32 v18, v17 offset:swizzle(SWAP,2)
	v_add3_u32 v24, v6, v24, s72
	s_waitcnt lgkmcnt(1)
	v_add_f32_e32 v6, v19, v23
	ds_swizzle_b32 v19, v6 offset:swizzle(SWAP,2)
	v_bfe_u32 v16, v7, 16, 1
	v_pk_fma_f32 v[4:5], v[0:1], v[4:5], v[2:3] op_sel:[1,0,1]
	v_add3_u32 v23, v7, v16, s72
	s_waitcnt lgkmcnt(1)
	v_add_f32_e32 v7, v17, v18
	v_bfe_u32 v13, v4, 16, 1
	ds_swizzle_b32 v16, v7 offset:swizzle(SWAP,4)
	v_add3_u32 v27, v4, v13, s72
	s_waitcnt lgkmcnt(1)
	v_add_f32_e32 v4, v6, v19
	ds_swizzle_b32 v6, v4 offset:swizzle(SWAP,4)
	v_bfe_u32 v12, v5, 16, 1
	v_add3_u32 v28, v5, v12, s72
	s_waitcnt lgkmcnt(1)
	v_add_f32_e32 v5, v7, v16
	ds_swizzle_b32 v7, v5 offset:swizzle(SWAP,8)
	s_waitcnt lgkmcnt(1)
	v_add_f32_e32 v4, v4, v6
	ds_swizzle_b32 v6, v4 offset:swizzle(SWAP,8)
	s_waitcnt vmcnt(1)
	v_lshlrev_b32_e32 v12, 16, v25
	v_and_b32_e32 v16, 0xffff0000, v25
	s_waitcnt lgkmcnt(1)
	v_add_f32_e32 v5, v5, v7
	ds_swizzle_b32 v7, v5 offset:swizzle(SWAP,16)
	s_waitcnt lgkmcnt(1)
	v_add_f32_e32 v4, v4, v6
	ds_swizzle_b32 v6, v4 offset:swizzle(SWAP,16)
	s_waitcnt vmcnt(0)
	v_lshlrev_b32_e32 v13, 16, v26
	v_and_b32_e32 v17, 0xffff0000, v26
	s_waitcnt lgkmcnt(1)
	v_add_f32_e32 v5, v5, v7
	v_add_f32_e32 v7, v13, v17
	v_readlane_b32 s0, v5, 0
	v_readlane_b32 s3, v5, 32
	v_add_f32_e32 v5, v12, v16
	s_waitcnt lgkmcnt(0)
	v_add_f32_e32 v4, v4, v6
	ds_swizzle_b32 v6, v5 offset:swizzle(SWAP,1)
	ds_swizzle_b32 v18, v7 offset:swizzle(SWAP,1)
	v_readlane_b32 s7, v4, 32
	v_readlane_b32 s1, v4, 0
	v_mov_b32_e32 v4, s3
	s_waitcnt lgkmcnt(1)
	v_add_f32_e32 v19, v5, v6
	v_mov_b32_e32 v5, s7
	v_pk_add_f32 v[4:5], s[0:1], v[4:5]
	s_waitcnt lgkmcnt(0)
	v_add_f32_e32 v18, v7, v18
	v_pk_fma_f32 v[6:7], v[4:5], s[12:13], v[8:9] op_sel_hi:[1,0,1] neg_lo:[1,0,0] neg_hi:[1,0,0]
	v_pk_fma_f32 v[4:5], v[4:5], s[12:13], v[10:11] op_sel_hi:[1,0,1] neg_lo:[1,0,0] neg_hi:[1,0,0]
	ds_swizzle_b32 v25, v19 offset:swizzle(SWAP,2)
	v_mul_f32_e32 v8, v4, v4
	v_fmac_f32_e32 v8, v6, v6
	ds_swizzle_b32 v9, v8 offset:swizzle(SWAP,1)
	ds_swizzle_b32 v26, v18 offset:swizzle(SWAP,2)
	s_waitcnt lgkmcnt(2)
	v_add_f32_e32 v10, v19, v25
	ds_swizzle_b32 v11, v10 offset:swizzle(SWAP,4)
	s_waitcnt lgkmcnt(2)
	v_add_f32_e32 v8, v8, v9
	s_waitcnt lgkmcnt(1)
	v_add_f32_e32 v18, v18, v26
	ds_swizzle_b32 v9, v8 offset:swizzle(SWAP,2)
	ds_swizzle_b32 v19, v18 offset:swizzle(SWAP,4)
	s_waitcnt lgkmcnt(2)
	v_add_f32_e32 v10, v10, v11
	ds_swizzle_b32 v11, v10 offset:swizzle(SWAP,8)
	s_waitcnt lgkmcnt(2)
	v_add_f32_e32 v8, v8, v9
	s_waitcnt lgkmcnt(1)
	v_add_f32_e32 v18, v18, v19
	ds_swizzle_b32 v9, v8 offset:swizzle(SWAP,4)
	ds_swizzle_b32 v19, v18 offset:swizzle(SWAP,8)
	s_waitcnt lgkmcnt(2)
	v_add_f32_e32 v10, v10, v11
	ds_swizzle_b32 v11, v10 offset:swizzle(SWAP,16)
	s_waitcnt lgkmcnt(2)
	v_add_f32_e32 v8, v8, v9
	s_waitcnt lgkmcnt(1)
	v_add_f32_e32 v18, v18, v19
	ds_swizzle_b32 v9, v8 offset:swizzle(SWAP,8)
	ds_swizzle_b32 v19, v18 offset:swizzle(SWAP,16)
	s_waitcnt lgkmcnt(2)
	v_add_f32_e32 v10, v10, v11
	s_waitcnt lgkmcnt(1)
	v_add_f32_e32 v11, v8, v9
	v_readlane_b32 s0, v10, 0
	v_readlane_b32 s3, v10, 32
	s_waitcnt lgkmcnt(0)
	v_add_f32_e32 v10, v18, v19
	ds_swizzle_b32 v18, v11 offset:swizzle(SWAP,16)
	v_readlane_b32 s1, v10, 0
	v_readlane_b32 s7, v10, 32
	v_mov_b32_e32 v8, s3
	s_waitcnt lgkmcnt(0)
	v_add_f32_e32 v10, v11, v18
	v_mul_f32_e32 v11, v5, v5
	v_fmac_f32_e32 v11, v7, v7
	ds_swizzle_b32 v18, v11 offset:swizzle(SWAP,1)
	v_mov_b32_e32 v9, s7
	v_readlane_b32 s7, v10, 32
	v_readlane_b32 s3, v10, 0
	v_pk_add_f32 v[8:9], s[0:1], v[8:9]
	s_waitcnt lgkmcnt(0)
	v_add_f32_e32 v11, v11, v18
	ds_swizzle_b32 v18, v11 offset:swizzle(SWAP,2)
	v_mov_b32_e32 v10, s7
	v_add_f32_e32 v10, s3, v10
	v_fmamk_f32 v10, v10, 0x3c000000, v197
	v_mul_f32_e32 v19, 0x4f800000, v10
	s_waitcnt lgkmcnt(0)
	v_add_f32_e32 v18, v11, v18
	ds_swizzle_b32 v26, v18 offset:swizzle(SWAP,4)
	v_cmp_gt_f32_e32 vcc, s61, v10
	s_nop 1
	v_cndmask_b32_e32 v19, v10, v19, vcc
	v_pk_fma_f32 v[10:11], v[8:9], s[12:13], v[12:13] op_sel_hi:[1,0,1] neg_lo:[1,0,0] neg_hi:[1,0,0]
	v_pk_fma_f32 v[12:13], v[8:9], s[12:13], v[16:17] op_sel_hi:[1,0,1] neg_lo:[1,0,0] neg_hi:[1,0,0]
	s_waitcnt lgkmcnt(0)
	v_add_f32_e32 v9, v18, v26
	ds_swizzle_b32 v16, v9 offset:swizzle(SWAP,8)
	v_sqrt_f32_e32 v25, v19
	s_waitcnt lgkmcnt(0)
	v_add_f32_e32 v9, v9, v16
	ds_swizzle_b32 v16, v9 offset:swizzle(SWAP,16)
	v_add_u32_e32 v8, -1, v25
	v_fma_f32 v17, -v8, v25, v19
	v_cmp_ge_f32_e64 s[0:1], 0, v17
	v_add_u32_e32 v17, 1, v25
	s_waitcnt lgkmcnt(0)
	v_add_f32_e32 v9, v9, v16
	v_mul_f32_e32 v16, v12, v12
	v_fma_f32 v18, -v17, v25, v19
	v_fmac_f32_e32 v16, v10, v10
	v_cndmask_b32_e64 v8, v25, v8, s[0:1]
	v_cmp_lt_f32_e64 s[0:1], 0, v18
	ds_swizzle_b32 v18, v16 offset:swizzle(SWAP,1)
	s_waitcnt lgkmcnt(0)
	v_add_f32_e32 v16, v16, v18
	ds_swizzle_b32 v18, v16 offset:swizzle(SWAP,2)
	v_cndmask_b32_e64 v8, v8, v17, s[0:1]
	v_readlane_b32 s1, v9, 32
	v_readlane_b32 s0, v9, 0
	v_mul_f32_e32 v17, 0x37800000, v8
	s_waitcnt lgkmcnt(0)
	v_add_f32_e32 v16, v16, v18
	ds_swizzle_b32 v18, v16 offset:swizzle(SWAP,4)
	v_mov_b32_e32 v9, s1
	v_add_f32_e32 v9, s0, v9
	v_fmamk_f32 v9, v9, 0x3c000000, v197
	v_mul_f32_e32 v25, 0x4f800000, v9
	s_waitcnt lgkmcnt(0)
; #define LAS __attribute__((address_space(3)))
; __device__ __forceinline__ unsigned f2bf(float f) { unsigned u = __builtin_bit_cast(unsigned, f); return (u + 0x7fffu + ((u >> 16) & 1u)) >> 16; }
; __device__ __forceinline__ void sgu_phase(const LArgs& a, LAS unsigned char* lds) {
;     ...
; #pragma unroll
;         for (int rr = 0; rr < 16; ++rr) {
;             const int r = wid * 16 + rr; const unsigned pk = *(const unsigned*)(Gg + (size_t)(row0 + r) * 1024 + g * 128 + 2 * lane);
;             const float x0 = bf2f(pk & 0xffffu), x1 = bf2f(pk >> 16);
;             const float mean = wave_sum(x0 + x1) * (1.f / 128.f); const float d0 = x0 - mean, d1 = x1 - mean;
;             const float rstd = 1.f / sqrtf(wave_sum(d0 * d0 + d1 * d1) * (1.f / 128.f) + 1e-5f);
;             *(LAS bf16*)(VVt + (2 * lane) * ROWB + r * 2) = (bf16)f2bf(d0 * rstd * ng0 + nb0); *(LAS bf16*)(VVt + (2 * lane + 1) * ROWB + r * 2) = (bf16)f2bf(d1 * rstd * ng1 + nb1);
;         }
;         __syncthreads();
	v_add_f32_e32 v16, v16, v18
	ds_swizzle_b32 v18, v16 offset:swizzle(SWAP,8)
	v_cmp_gt_f32_e64 s[0:1], s61, v9
	v_cndmask_b32_e32 v8, v8, v17, vcc
	v_cmp_class_f32_e32 vcc, v19, v194
	v_cndmask_b32_e64 v9, v9, v25, s[0:1]
	v_sqrt_f32_e32 v25, v9
	s_waitcnt lgkmcnt(0)
	v_add_f32_e32 v16, v16, v18
	ds_swizzle_b32 v18, v16 offset:swizzle(SWAP,16)
	v_cndmask_b32_e32 v8, v8, v19, vcc
	v_add_u32_e32 v17, -1, v25
	v_fma_f32 v19, -v17, v25, v9
	v_cmp_ge_f32_e32 vcc, 0, v19
	v_add_u32_e32 v19, 1, v25
	s_waitcnt lgkmcnt(0)
	v_add_f32_e32 v16, v16, v18
	v_mul_f32_e32 v18, v13, v13
	v_cndmask_b32_e32 v17, v25, v17, vcc
	v_fma_f32 v25, -v19, v25, v9
	v_fmac_f32_e32 v18, v11, v11
	v_cmp_lt_f32_e32 vcc, 0, v25
	ds_swizzle_b32 v25, v18 offset:swizzle(SWAP,1)
	v_readlane_b32 s7, v16, 32
	v_cndmask_b32_e32 v17, v17, v19, vcc
	v_readlane_b32 s3, v16, 0
	v_mov_b32_e32 v16, s7
	s_waitcnt lgkmcnt(0)
	v_add_f32_e32 v18, v18, v25
	ds_swizzle_b32 v25, v18 offset:swizzle(SWAP,2)
	v_mul_f32_e32 v19, 0x37800000, v17
	v_add_f32_e32 v16, s3, v16
	v_fmamk_f32 v16, v16, 0x3c000000, v197
	v_cndmask_b32_e64 v17, v17, v19, s[0:1]
	s_waitcnt lgkmcnt(0)
	v_add_f32_e32 v18, v18, v25
	ds_swizzle_b32 v25, v18 offset:swizzle(SWAP,4)
	v_mul_f32_e32 v26, 0x4f800000, v16
	v_cmp_gt_f32_e32 vcc, s61, v16
	v_cmp_class_f32_e64 s[0:1], v9, v194
	s_mov_b32 s3, 0x1d000000
	s_waitcnt lgkmcnt(0)
	v_add_f32_e32 v18, v18, v25
	ds_swizzle_b32 v19, v18 offset:swizzle(SWAP,8)
	v_cndmask_b32_e32 v16, v16, v26, vcc
	v_sqrt_f32_e32 v26, v16
	v_cndmask_b32_e64 v9, v17, v9, s[0:1]
	s_mov_b64 s[6:7], 0x1d000800
	s_waitcnt lgkmcnt(0)
	v_add_f32_e32 v18, v18, v19
	ds_swizzle_b32 v19, v18 offset:swizzle(SWAP,16)
	v_add_u32_e32 v17, -1, v26
	v_fma_f32 v25, -v17, v26, v16
	v_cmp_ge_f32_e64 s[0:1], 0, v25
	v_add_u32_e32 v25, 1, v26
	s_waitcnt lgkmcnt(0)
	v_add_f32_e32 v18, v18, v19
	v_cndmask_b32_e64 v17, v26, v17, s[0:1]
	v_fma_f32 v26, -v25, v26, v16
	v_cmp_lt_f32_e64 s[0:1], 0, v26
	s_nop 1
	v_cndmask_b32_e64 v17, v17, v25, s[0:1]
	v_readlane_b32 s1, v18, 32
	v_readlane_b32 s0, v18, 0
	v_mul_f32_e32 v25, 0x37800000, v17
	v_mov_b32_e32 v18, s1
	v_add_f32_e32 v18, s0, v18
	v_fmamk_f32 v18, v18, 0x3c000000, v197
	v_mul_f32_e32 v19, 0x4f800000, v18
	v_cmp_gt_f32_e64 s[0:1], s61, v18
	v_cndmask_b32_e32 v17, v17, v25, vcc
	v_cmp_class_f32_e32 vcc, v16, v194
	v_cndmask_b32_e64 v18, v18, v19, s[0:1]
	v_sqrt_f32_e32 v19, v18
	v_cndmask_b32_e32 v25, v17, v16, vcc
	v_add_u32_e32 v16, -1, v19
	v_fma_f32 v17, -v16, v19, v18
	v_cmp_ge_f32_e32 vcc, 0, v17
	v_add_u32_e32 v17, 1, v19
	s_nop 0
	v_cndmask_b32_e32 v16, v19, v16, vcc
	v_fma_f32 v19, -v17, v19, v18
	v_cmp_lt_f32_e32 vcc, 0, v19
	v_div_scale_f32 v19, s[8:9], v9, v9, 1.0
	v_rcp_f32_e32 v26, v19
	v_cndmask_b32_e32 v16, v16, v17, vcc
	v_mul_f32_e32 v17, 0x37800000, v16
	v_cndmask_b32_e64 v16, v16, v17, s[0:1]
	v_cmp_class_f32_e32 vcc, v18, v194
	v_readlane_b32 s8, v254, 35
	v_readlane_b32 s9, v254, 36
	v_cndmask_b32_e32 v18, v16, v18, vcc
	v_fma_f32 v16, -v19, v26, 1.0
	v_fmac_f32_e32 v26, v16, v26
	v_div_scale_f32 v16, vcc, 1.0, v9, 1.0
	v_mul_f32_e32 v17, v16, v26
	v_fma_f32 v29, -v19, v17, v16
	v_fmac_f32_e32 v17, v29, v26
	v_fma_f32 v16, -v19, v17, v16
	v_div_scale_f32 v19, s[0:1], v8, v8, 1.0
	v_rcp_f32_e32 v29, v19
	v_div_fmas_f32 v16, v16, v26, v17
	v_div_fixup_f32 v17, v16, v9, 1.0
	v_fma_f32 v9, -v19, v29, 1.0
	v_fmac_f32_e32 v29, v9, v29
	v_div_scale_f32 v9, vcc, 1.0, v8, 1.0
	v_mul_f32_e32 v16, v9, v29
	v_fma_f32 v26, -v19, v16, v9
	v_fmac_f32_e32 v16, v26, v29
	v_fma_f32 v9, -v19, v16, v9
	v_div_scale_f32 v19, s[0:1], v18, v18, 1.0
	v_rcp_f32_e32 v26, v19
	v_div_fmas_f32 v9, v9, v29, v16
	v_div_fixup_f32 v16, v9, v8, 1.0
	v_pk_mul_f32 v[6:7], v[6:7], v[16:17]
	v_fma_f32 v8, -v19, v26, 1.0
	v_fmac_f32_e32 v26, v8, v26
	v_div_scale_f32 v8, vcc, 1.0, v18, 1.0
	v_mul_f32_e32 v9, v8, v26
	v_fma_f32 v29, -v19, v9, v8
	v_fmac_f32_e32 v9, v29, v26
	v_div_scale_f32 v29, s[0:1], v25, v25, 1.0
	v_rcp_f32_e32 v30, v29
	v_fma_f32 v8, -v19, v9, v8
	v_div_fmas_f32 v8, v8, v26, v9
	v_div_fixup_f32 v19, v8, v18, 1.0
	v_fma_f32 v8, -v29, v30, 1.0
	v_fmac_f32_e32 v30, v8, v30
	v_div_scale_f32 v8, vcc, 1.0, v25, 1.0
	v_mul_f32_e32 v9, v8, v30
	v_fma_f32 v18, -v29, v9, v8
	v_fmac_f32_e32 v9, v18, v30
	v_fma_f32 v8, -v29, v9, v8
	v_div_fmas_f32 v8, v8, v30, v9
	v_div_fixup_f32 v18, v8, v25, 1.0
	v_pk_mul_f32 v[8:9], v[10:11], v[18:19]
	v_pk_fma_f32 v[6:7], v[0:1], v[6:7], v[2:3] op_sel_hi:[0,1,0]
	v_pk_fma_f32 v[8:9], v[0:1], v[8:9], v[2:3] op_sel_hi:[0,1,0]
	v_bfe_u32 v10, v9, 16, 1
	v_bfe_u32 v11, v8, 16, 1
	v_bfe_u32 v25, v7, 16, 1
	v_bfe_u32 v26, v6, 16, 1
	v_add3_u32 v6, v6, v26, s72
	v_add3_u32 v7, v7, v25, s72
	v_add3_u32 v8, v8, v11, s72
	v_add3_u32 v9, v9, v10, s72
	v_perm_b32 v9, v9, v8, s10
	v_perm_b32 v8, v7, v6, s10
	v_perm_b32 v7, v15, v22, s10
	v_perm_b32 v6, v21, v20, s10
	ds_write_b128 v72, v[6:9] offset:34816
	v_pk_mul_f32 v[6:7], v[12:13], v[18:19]
	v_pk_mul_f32 v[4:5], v[4:5], v[16:17]
	s_nop 0
	v_pk_fma_f32 v[4:5], v[0:1], v[4:5], v[2:3] op_sel:[1,0,1]
	v_pk_fma_f32 v[0:1], v[0:1], v[6:7], v[2:3] op_sel:[1,0,1]
	v_bfe_u32 v6, v5, 16, 1
	v_bfe_u32 v2, v1, 16, 1
	v_bfe_u32 v3, v0, 16, 1
	v_bfe_u32 v7, v4, 16, 1
	v_add3_u32 v4, v4, v7, s72
	v_add3_u32 v5, v5, v6, s72
	v_add3_u32 v0, v0, v3, s72
	v_add3_u32 v1, v1, v2, s72
	v_perm_b32 v3, v1, v0, s10
	v_perm_b32 v2, v5, v4, s10
	v_perm_b32 v1, v28, v27, s10
	v_perm_b32 v0, v23, v24, s10
	ds_write_b128 v72, v[0:3] offset:35088
	s_waitcnt lgkmcnt(0)
	s_barrier
; #define LAS __attribute__((address_space(3)))
; __device__ __forceinline__ unsigned pk2(float lo, float hi) { return f2bf(lo) | (f2bf(hi) << 16); }
; __device__ __forceinline__ void sgu_phase(const LArgs& a, LAS unsigned char* lds) {
;     ...
; #pragma unroll
;         for (int ks = 0; ks < 8; ++ks) {
;             const bf16x8 af = *(const LAS bf16x8*)(VVt + (32 * cblk + r32) * ROWB + ks * 32 + hi * 16);
; #pragma unroll
;             for (int i = 0; i < 2; ++i) { const int pblk = (wid & 1) * 2 + i; const bf16x8 bfr = *(const LAS bf16x8*)(WsB + (32 * pblk + r32) * ROWB + ks * 32 + hi * 16);
;                 acc[i] = __builtin_amdgcn_mfma_f32_32x32x16_bf16(af, bfr, acc[i], 0, 0, 0); }
;         }
; #pragma unroll
;         for (int i = 0; i < 2; ++i) {
;             const int p = 32 * ((wid & 1) * 2 + i) + r32; const float bs = a.in(I_ESB)[g * 128 + p];
;             const bf16* up = Ug + (size_t)(row0 + p) * 1024 + g * 128 + 32 * cblk + 4 * hi; bf16* op = act + (size_t)(row0 + p) * DM + 1024 + g * 128 + 32 * cblk + 4 * hi;
; #pragma unroll
;             for (int j4 = 0; j4 < 4; ++j4) {
;                 const u32x2 uu = *(const u32x2*)(up + 8 * j4);
;                 const f32x4 mix = {acc[i][4 * j4 + 0] + bs, acc[i][4 * j4 + 1] + bs, acc[i][4 * j4 + 2] + bs, acc[i][4 * j4 + 3] + bs};
;                 const f32x4 o = (f32x4){bf2f(uu.x & 0xffffu), bf2f(uu.x >> 16), bf2f(uu.y & 0xffffu), bf2f(uu.y >> 16)} * mix;
;                 u32x2 w; w.x = pk2(o.x, o.y); w.y = pk2(o.z, o.w); *(u32x2*)(op + 8 * j4) = w;
;             }
	ds_read_b128 v[0:3], v73 offset:34816
	ds_read_b128 v[4:7], v74
	ds_read_b128 v[32:35], v73 offset:35040
	ds_read_b64 v[104:105], v14 offset:144
	s_waitcnt lgkmcnt(2)
	v_mfma_f32_32x32x16_bf16 v[16:31], v[0:3], v[4:7], 0
	ds_read_b128 v[4:7], v74 offset:8704
	ds_read_b128 v[76:79], v74 offset:224
	ds_read_b128 v[80:83], v73 offset:34848
	ds_read_b128 v[84:87], v74 offset:32
	ds_read_b128 v[88:91], v73 offset:34880
	ds_read_b128 v[92:95], v74 offset:64
	s_waitcnt lgkmcnt(6)
	v_readfirstlane_b32 s1, v105
	v_readfirstlane_b32 s0, v104
	s_waitcnt lgkmcnt(5)
	v_mfma_f32_32x32x16_bf16 v[0:15], v[0:3], v[4:7], 0
	s_waitcnt lgkmcnt(2)
	v_mfma_f32_32x32x16_bf16 v[16:31], v[80:83], v[84:87], v[16:31]
	ds_read_b128 v[84:87], v74 offset:8736
	ds_read_b128 v[96:99], v74 offset:8768
	s_waitcnt lgkmcnt(1)
	v_mfma_f32_32x32x16_bf16 v[0:15], v[80:83], v[84:87], v[0:15]
	v_mfma_f32_32x32x16_bf16 v[16:31], v[88:91], v[92:95], v[16:31]
	s_waitcnt lgkmcnt(0)
	v_mfma_f32_32x32x16_bf16 v[0:15], v[88:91], v[96:99], v[0:15]
	ds_read_b128 v[80:83], v73 offset:34912
	ds_read_b128 v[84:87], v74 offset:96
	ds_read_b128 v[88:91], v73 offset:34944
	ds_read_b128 v[92:95], v74 offset:128
	s_waitcnt lgkmcnt(2)
	v_mfma_f32_32x32x16_bf16 v[16:31], v[80:83], v[84:87], v[16:31]
	ds_read_b128 v[84:87], v74 offset:8800
	ds_read_b128 v[96:99], v74 offset:8832
	s_waitcnt lgkmcnt(2)
	v_mfma_f32_32x32x16_bf16 v[16:31], v[88:91], v[92:95], v[16:31]
	s_waitcnt lgkmcnt(1)
	v_mfma_f32_32x32x16_bf16 v[0:15], v[80:83], v[84:87], v[0:15]
	ds_read_b128 v[80:83], v73 offset:34976
	ds_read_b128 v[84:87], v74 offset:160
	ds_read_b128 v[92:95], v73 offset:35008
	ds_read_b128 v[100:103], v74 offset:192
	s_waitcnt lgkmcnt(2)
	v_mfma_f32_32x32x16_bf16 v[16:31], v[80:83], v[84:87], v[16:31]
	v_lshl_add_u64 v[84:85], v[40:41], 0, s[48:49]
	global_load_dword v86, v75, s[0:1]
	s_waitcnt lgkmcnt(0)
	v_mfma_f32_32x32x16_bf16 v[16:31], v[92:95], v[100:103], v[16:31]
	v_or_b32_e32 v100, s5, v61
	v_ashrrev_i32_e32 v101, 31, v100
	v_lshlrev_b64 v[102:103], 11, v[100:101]
	v_lshl_add_u64 v[102:103], v[84:85], 0, v[102:103]
	global_load_dwordx2 v[104:105], v[102:103], off
	global_load_dwordx2 v[106:107], v[102:103], off offset:16
	global_load_dwordx2 v[108:109], v[102:103], off offset:32
	global_load_dwordx2 v[110:111], v[102:103], off offset:48
	v_mfma_f32_32x32x16_bf16 v[16:31], v[32:35], v[76:79], v[16:31]
	v_lshlrev_b64 v[76:77], 12, v[100:101]
	v_lshl_add_u64 v[76:77], s[8:9], 0, v[76:77]
	v_lshl_add_u64 v[76:77], v[76:77], 0, s[48:49]
	v_lshl_add_u64 v[76:77], v[76:77], 0, v[42:43]
	v_lshl_add_u64 v[76:77], v[76:77], 0, v[172:173]
	s_waitcnt vmcnt(4)
	s_nop 5
	v_pk_add_f32 v[16:17], v[16:17], v[86:87] op_sel_hi:[1,0]
	v_pk_add_f32 v[18:19], v[18:19], v[86:87] op_sel_hi:[1,0]
	v_mfma_f32_32x32x16_bf16 v[0:15], v[88:91], v[96:99], v[0:15]
	s_waitcnt vmcnt(3)
	v_lshlrev_b32_e32 v78, 16, v104
	v_and_b32_e32 v79, 0xffff0000, v104
	v_mul_f32_e64 v16, v16, v78
	v_mul_f32_e64 v17, v17, v79
	v_lshlrev_b32_e32 v100, 16, v105
	v_bfe_u32 v78, v16, 16, 1
	v_and_b32_e32 v101, 0xffff0000, v105
	v_add3_u32 v16, v16, v78, s72
	v_bfe_u32 v78, v17, 16, 1
	v_pk_mul_f32 v[18:19], v[18:19], v[100:101]
	v_lshrrev_b32_e32 v16, 16, v16
	v_add3_u32 v17, v17, v78, s72
	v_and_or_b32 v16, v17, s73, v16
	v_bfe_u32 v17, v18, 16, 1
	v_add3_u32 v17, v18, v17, s72
	v_bfe_u32 v18, v19, 16, 1
	v_lshrrev_b32_e32 v17, 16, v17
	v_add3_u32 v18, v19, v18, s72
	v_and_or_b32 v17, v18, s73, v17
	v_add_co_u32_e32 v18, vcc, s3, v76
	s_nop 1
	v_addc_co_u32_e32 v19, vcc, 0, v77, vcc
	global_store_dwordx2 v[18:19], v[16:17], off offset:2048
	v_pk_add_f32 v[18:19], v[20:21], v[86:87] op_sel_hi:[1,0]
	v_pk_add_f32 v[20:21], v[22:23], v[86:87] op_sel_hi:[1,0]
	v_lshl_add_u64 v[76:77], v[76:77], 0, s[6:7]
	s_waitcnt vmcnt(3)
	v_mov_b32_e32 v16, v106
	v_mov_b32_e32 v17, v107
	v_lshlrev_b32_e32 v22, 16, v16
	v_and_b32_e32 v23, 0xffff0000, v16
	v_lshlrev_b32_e32 v16, 16, v17
	v_and_b32_e32 v17, 0xffff0000, v17
	v_pk_mul_f32 v[18:19], v[18:19], v[22:23]
	v_pk_mul_f32 v[16:17], v[20:21], v[16:17]
	v_bfe_u32 v20, v18, 16, 1
	v_add3_u32 v18, v18, v20, s72
	v_bfe_u32 v20, v19, 16, 1
	v_lshrrev_b32_e32 v18, 16, v18
	v_add3_u32 v19, v19, v20, s72
	v_and_or_b32 v18, v19, s73, v18
	v_bfe_u32 v19, v16, 16, 1
	v_add3_u32 v16, v16, v19, s72
	v_bfe_u32 v19, v17, 16, 1
	v_lshrrev_b32_e32 v16, 16, v16
	v_add3_u32 v17, v17, v19, s72
	v_and_or_b32 v19, v17, s73, v16
	global_store_dwordx2 v[76:77], v[18:19], off offset:16
	ds_read_b128 v[16:19], v74 offset:8864
	ds_read_b128 v[20:23], v74 offset:8896
	s_waitcnt lgkmcnt(1)
	v_mfma_f32_32x32x16_bf16 v[0:15], v[80:83], v[16:19], v[0:15]
	v_add_f32_e64 v16, v24, v86
	v_add_f32_e64 v17, v25, v86
	v_add_f32_e64 v18, v26, v86
	v_add_f32_e64 v19, v27, v86
	s_waitcnt vmcnt(3)
	v_mov_b32_e32 v78, v108
	v_mov_b32_e32 v79, v109
	v_lshlrev_b32_e32 v24, 16, v78
	v_and_b32_e32 v25, 0xffff0000, v78
	v_pk_mul_f32 v[16:17], v[16:17], v[24:25]
	v_lshlrev_b32_e32 v26, 16, v79
	v_bfe_u32 v24, v16, 16, 1
	v_and_b32_e32 v27, 0xffff0000, v79
	v_add3_u32 v16, v16, v24, s72
	v_bfe_u32 v24, v17, 16, 1
	v_pk_mul_f32 v[18:19], v[18:19], v[26:27]
	v_lshrrev_b32_e32 v16, 16, v16
	v_add3_u32 v17, v17, v24, s72
	v_and_or_b32 v16, v17, s73, v16
	v_bfe_u32 v17, v18, 16, 1
	v_add3_u32 v17, v18, v17, s72
	v_bfe_u32 v18, v19, 16, 1
	v_lshrrev_b32_e32 v17, 16, v17
	v_add3_u32 v18, v19, v18, s72
	v_and_or_b32 v17, v18, s73, v17
	global_store_dwordx2 v[76:77], v[16:17], off offset:32
	s_waitcnt lgkmcnt(0)
; __device__ __forceinline__ unsigned pk2(float lo, float hi) { return f2bf(lo) | (f2bf(hi) << 16); }
; __device__ __forceinline__ void sgu_phase(const LArgs& a, LAS unsigned char* lds) {
;     ...
; #pragma unroll
;         for (int i = 0; i < 2; ++i) {
;             const int p = 32 * ((wid & 1) * 2 + i) + r32; const float bs = a.in(I_ESB)[g * 128 + p];
;             const bf16* up = Ug + (size_t)(row0 + p) * 1024 + g * 128 + 32 * cblk + 4 * hi; bf16* op = act + (size_t)(row0 + p) * DM + 1024 + g * 128 + 32 * cblk + 4 * hi;
; #pragma unroll
;             for (int j4 = 0; j4 < 4; ++j4) {
;                 const u32x2 uu = *(const u32x2*)(up + 8 * j4);
;                 const f32x4 mix = {acc[i][4 * j4 + 0] + bs, acc[i][4 * j4 + 1] + bs, acc[i][4 * j4 + 2] + bs, acc[i][4 * j4 + 3] + bs};
;                 const f32x4 o = (f32x4){bf2f(uu.x & 0xffffu), bf2f(uu.x >> 16), bf2f(uu.y & 0xffffu), bf2f(uu.y >> 16)} * mix;
;                 u32x2 w; w.x = pk2(o.x, o.y); w.y = pk2(o.z, o.w); *(u32x2*)(op + 8 * j4) = w;
;             }
;         }
;         __syncthreads();
;     }
	v_mfma_f32_32x32x16_bf16 v[0:15], v[92:95], v[20:23], v[0:15]
	v_add_f32_e64 v18, v28, v86
	v_add_f32_e64 v19, v29, v86
	v_add_f32_e64 v20, v30, v86
	v_add_f32_e64 v21, v31, v86
	s_waitcnt vmcnt(3)
	v_mov_b32_e32 v16, v110
	v_mov_b32_e32 v17, v111
	v_lshlrev_b32_e32 v22, 16, v16
	v_and_b32_e32 v23, 0xffff0000, v16
	v_lshlrev_b32_e32 v16, 16, v17
	v_and_b32_e32 v17, 0xffff0000, v17
	v_pk_mul_f32 v[18:19], v[18:19], v[22:23]
	v_pk_mul_f32 v[16:17], v[20:21], v[16:17]
	v_bfe_u32 v20, v18, 16, 1
	v_add3_u32 v18, v18, v20, s72
	v_bfe_u32 v20, v19, 16, 1
	v_lshrrev_b32_e32 v18, 16, v18
	v_add3_u32 v19, v19, v20, s72
	v_and_or_b32 v18, v19, s73, v18
	v_bfe_u32 v19, v16, 16, 1
	v_add3_u32 v16, v16, v19, s72
	v_bfe_u32 v19, v17, 16, 1
	v_or_b32_e32 v22, s5, v62
	v_lshrrev_b32_e32 v16, 16, v16
	v_add3_u32 v17, v17, v19, s72
	v_ashrrev_i32_e32 v23, 31, v22
	v_and_or_b32 v19, v17, s73, v16
	v_lshlrev_b64 v[16:17], 11, v[22:23]
	global_store_dwordx2 v[76:77], v[18:19], off offset:48
	v_lshl_add_u64 v[24:25], v[84:85], 0, v[16:17]
	global_load_dword v20, v75, s[0:1] offset:128
	global_load_dwordx2 v[26:27], v[24:25], off
	global_load_dwordx2 v[112:113], v[24:25], off offset:16
	global_load_dwordx2 v[114:115], v[24:25], off offset:32
	global_load_dwordx2 v[116:117], v[24:25], off offset:48
	ds_read_b128 v[16:19], v74 offset:8928
	s_waitcnt lgkmcnt(0)
	v_mfma_f32_32x32x16_bf16 v[0:15], v[32:35], v[16:19], v[0:15]
	v_lshlrev_b64 v[16:17], 12, v[22:23]
	v_lshl_add_u64 v[16:17], s[8:9], 0, v[16:17]
	v_lshl_add_u64 v[16:17], v[16:17], 0, s[48:49]
	v_lshl_add_u64 v[16:17], v[16:17], 0, v[42:43]
	v_lshl_add_u64 v[16:17], v[16:17], 0, v[172:173]
	s_mov_b64 s[0:1], -1
	s_waitcnt vmcnt(4)
	s_nop 4
	v_pk_add_f32 v[0:1], v[0:1], v[20:21] op_sel_hi:[1,0]
	s_waitcnt vmcnt(3)
	v_lshlrev_b32_e32 v18, 16, v26
	v_and_b32_e32 v19, 0xffff0000, v26
	v_pk_mul_f32 v[0:1], v[0:1], v[18:19]
	v_pk_add_f32 v[2:3], v[2:3], v[20:21] op_sel_hi:[1,0]
	v_bfe_u32 v18, v0, 16, 1
	v_lshlrev_b32_e32 v22, 16, v27
	v_and_b32_e32 v23, 0xffff0000, v27
	v_add3_u32 v0, v0, v18, s72
	v_bfe_u32 v18, v1, 16, 1
	v_pk_mul_f32 v[2:3], v[2:3], v[22:23]
	v_lshrrev_b32_e32 v0, 16, v0
	v_add3_u32 v1, v1, v18, s72
	v_and_or_b32 v0, v1, s73, v0
	v_bfe_u32 v1, v2, 16, 1
	v_add3_u32 v1, v2, v1, s72
	v_bfe_u32 v2, v3, 16, 1
	v_lshrrev_b32_e32 v1, 16, v1
	v_add3_u32 v2, v3, v2, s72
	v_and_or_b32 v1, v2, s73, v1
	v_add_co_u32_e32 v2, vcc, s3, v16
	v_pk_add_f32 v[4:5], v[4:5], v[20:21] op_sel_hi:[1,0]
	s_nop 0
	v_addc_co_u32_e32 v3, vcc, 0, v17, vcc
	global_store_dwordx2 v[2:3], v[0:1], off offset:2048
	v_lshl_add_u64 v[2:3], v[16:17], 0, s[6:7]
	v_pk_add_f32 v[6:7], v[6:7], v[20:21] op_sel_hi:[1,0]
	s_waitcnt vmcnt(3)
	v_mov_b32_e32 v0, v112
	v_mov_b32_e32 v1, v113
	v_lshlrev_b32_e32 v16, 16, v0
	v_and_b32_e32 v17, 0xffff0000, v0
	v_lshlrev_b32_e32 v0, 16, v1
	v_and_b32_e32 v1, 0xffff0000, v1
	v_pk_mul_f32 v[4:5], v[4:5], v[16:17]
	v_pk_mul_f32 v[0:1], v[6:7], v[0:1]
	v_bfe_u32 v6, v4, 16, 1
	v_add3_u32 v4, v4, v6, s72
	v_bfe_u32 v6, v5, 16, 1
	v_lshrrev_b32_e32 v4, 16, v4
	v_add3_u32 v5, v5, v6, s72
	v_and_or_b32 v4, v5, s73, v4
	v_bfe_u32 v5, v0, 16, 1
	v_add3_u32 v0, v0, v5, s72
	v_bfe_u32 v5, v1, 16, 1
	v_lshrrev_b32_e32 v0, 16, v0
	v_add3_u32 v1, v1, v5, s72
	v_and_or_b32 v5, v1, s73, v0
	global_store_dwordx2 v[2:3], v[4:5], off offset:16
	v_pk_add_f32 v[4:5], v[8:9], v[20:21] op_sel_hi:[1,0]
	v_pk_add_f32 v[6:7], v[10:11], v[20:21] op_sel_hi:[1,0]
	s_waitcnt vmcnt(3)
	v_mov_b32_e32 v0, v114
	v_mov_b32_e32 v1, v115
	v_lshlrev_b32_e32 v8, 16, v0
	v_and_b32_e32 v9, 0xffff0000, v0
	v_lshlrev_b32_e32 v0, 16, v1
	v_and_b32_e32 v1, 0xffff0000, v1
	v_pk_mul_f32 v[4:5], v[4:5], v[8:9]
	v_pk_mul_f32 v[0:1], v[6:7], v[0:1]
	v_bfe_u32 v6, v4, 16, 1
	v_add3_u32 v4, v4, v6, s72
	v_bfe_u32 v6, v5, 16, 1
	v_lshrrev_b32_e32 v4, 16, v4
	v_add3_u32 v5, v5, v6, s72
	v_and_or_b32 v4, v5, s73, v4
	v_bfe_u32 v5, v0, 16, 1
	v_add3_u32 v0, v0, v5, s72
	v_bfe_u32 v5, v1, 16, 1
	v_lshrrev_b32_e32 v0, 16, v0
	v_add3_u32 v1, v1, v5, s72
	v_and_or_b32 v5, v1, s73, v0
	global_store_dwordx2 v[2:3], v[4:5], off offset:32
	v_pk_add_f32 v[4:5], v[12:13], v[20:21] op_sel_hi:[1,0]
	v_pk_add_f32 v[6:7], v[14:15], v[20:21] op_sel_hi:[1,0]
	s_waitcnt vmcnt(3)
	v_mov_b32_e32 v0, v116
	v_mov_b32_e32 v1, v117
	v_lshlrev_b32_e32 v8, 16, v0
	v_and_b32_e32 v9, 0xffff0000, v0
	v_lshlrev_b32_e32 v0, 16, v1
	v_and_b32_e32 v1, 0xffff0000, v1
	v_pk_mul_f32 v[4:5], v[4:5], v[8:9]
	v_pk_mul_f32 v[0:1], v[6:7], v[0:1]
	v_bfe_u32 v6, v4, 16, 1
	v_add3_u32 v4, v4, v6, s72
	v_bfe_u32 v6, v5, 16, 1
	v_lshrrev_b32_e32 v4, 16, v4
	v_add3_u32 v5, v5, v6, s72
	v_and_or_b32 v4, v5, s73, v4
	v_bfe_u32 v5, v0, 16, 1
	v_add3_u32 v0, v0, v5, s72
	v_bfe_u32 v5, v1, 16, 1
	v_lshrrev_b32_e32 v0, 16, v0
	v_add3_u32 v1, v1, v5, s72
	v_and_or_b32 v5, v1, s73, v0
	global_store_dwordx2 v[2:3], v[4:5], off offset:48
	s_barrier
	s_cbranch_scc1 .LBB0_314
